# K loops: last two LDS-DMA loads of each 6-load sub-phase slip past the wait/barrier/MFMA block into the start of the next sub-phase (issue order unchanged; the passed wait becomes vmcnt(6))
# speedup vs baseline: 1.0010x; 1.0010x over previous
.LBB0_276:
	s_and_b64 s[30:31], s[20:21], exec
	s_cselect_b32 s2, s17, s27
	s_cselect_b32 s13, s16, s26
	s_cselect_b32 s15, s19, s29
	s_cselect_b32 s23, s18, s28
	s_add_u32 s26, s26, 0x80080
	s_addc_u32 s27, s27, 0
	s_add_u32 s25, s28, 0x100
	v_mov_b32_e32 v2, 0
	s_addc_u32 s33, s29, 0
	s_mov_b32 s50, -2
	v_mov_b32_e32 v3, v2
	v_mov_b32_e32 v4, v2
	v_mov_b32_e32 v5, v2
	v_mov_b32_e32 v6, v2
	v_mov_b32_e32 v7, v2
	v_mov_b32_e32 v8, v2
	v_mov_b32_e32 v9, v2
	v_mov_b32_e32 v18, v2
	v_mov_b32_e32 v19, v2
	v_mov_b32_e32 v20, v2
	v_mov_b32_e32 v21, v2
	v_mov_b32_e32 v22, v2
	v_mov_b32_e32 v23, v2
	v_mov_b32_e32 v24, v2
	v_mov_b32_e32 v25, v2
	v_mov_b32_e32 v34, v2
	v_mov_b32_e32 v35, v2
	v_mov_b32_e32 v36, v2
	v_mov_b32_e32 v37, v2
	v_mov_b32_e32 v38, v2
	v_mov_b32_e32 v39, v2
	v_mov_b32_e32 v40, v2
	v_mov_b32_e32 v41, v2
	v_mov_b32_e32 v50, v2
	v_mov_b32_e32 v51, v2
	v_mov_b32_e32 v52, v2
	v_mov_b32_e32 v53, v2
	v_mov_b32_e32 v54, v2
	v_mov_b32_e32 v55, v2
	v_mov_b32_e32 v56, v2
	v_mov_b32_e32 v57, v2
	v_mov_b32_e32 v10, v2
	v_mov_b32_e32 v11, v2
	v_mov_b32_e32 v12, v2
	v_mov_b32_e32 v13, v2
	v_mov_b32_e32 v14, v2
	v_mov_b32_e32 v15, v2
	v_mov_b32_e32 v16, v2
	v_mov_b32_e32 v17, v2
	v_mov_b32_e32 v26, v2
	v_mov_b32_e32 v27, v2
	v_mov_b32_e32 v28, v2
	v_mov_b32_e32 v29, v2
	v_mov_b32_e32 v30, v2
	v_mov_b32_e32 v31, v2
	v_mov_b32_e32 v32, v2
	v_mov_b32_e32 v33, v2
	v_mov_b32_e32 v42, v2
	v_mov_b32_e32 v43, v2
	v_mov_b32_e32 v44, v2
	v_mov_b32_e32 v45, v2
	v_mov_b32_e32 v46, v2
	v_mov_b32_e32 v47, v2
	v_mov_b32_e32 v48, v2
	v_mov_b32_e32 v49, v2
	v_mov_b32_e32 v58, v2
	v_mov_b32_e32 v59, v2
	v_mov_b32_e32 v60, v2
	v_mov_b32_e32 v61, v2
	v_mov_b32_e32 v62, v2
	v_mov_b32_e32 v63, v2
	v_mov_b32_e32 v64, v2
	v_mov_b32_e32 v65, v2
	v_mov_b32_e32 v66, v2
	v_mov_b32_e32 v67, v2
	v_mov_b32_e32 v68, v2
	v_mov_b32_e32 v69, v2
	v_mov_b32_e32 v70, v2
	v_mov_b32_e32 v71, v2
	v_mov_b32_e32 v72, v2
	v_mov_b32_e32 v73, v2
	v_mov_b32_e32 v82, v2
	v_mov_b32_e32 v83, v2
	v_mov_b32_e32 v84, v2
	v_mov_b32_e32 v85, v2
	v_mov_b32_e32 v86, v2
	v_mov_b32_e32 v87, v2
	v_mov_b32_e32 v88, v2
	v_mov_b32_e32 v89, v2
	v_mov_b32_e32 v98, v2
	v_mov_b32_e32 v99, v2
	v_mov_b32_e32 v100, v2
	v_mov_b32_e32 v101, v2
	v_mov_b32_e32 v102, v2
	v_mov_b32_e32 v103, v2
	v_mov_b32_e32 v104, v2
	v_mov_b32_e32 v105, v2
	v_mov_b32_e32 v114, v2
	v_mov_b32_e32 v115, v2
	v_mov_b32_e32 v116, v2
	v_mov_b32_e32 v117, v2
	v_mov_b32_e32 v118, v2
	v_mov_b32_e32 v119, v2
	v_mov_b32_e32 v120, v2
	v_mov_b32_e32 v121, v2
	v_mov_b32_e32 v74, v2
	v_mov_b32_e32 v75, v2
	v_mov_b32_e32 v76, v2
	v_mov_b32_e32 v77, v2
	v_mov_b32_e32 v78, v2
	v_mov_b32_e32 v79, v2
	v_mov_b32_e32 v80, v2
	v_mov_b32_e32 v81, v2
	v_mov_b32_e32 v90, v2
	v_mov_b32_e32 v91, v2
	v_mov_b32_e32 v92, v2
	v_mov_b32_e32 v93, v2
	v_mov_b32_e32 v94, v2
	v_mov_b32_e32 v95, v2
	v_mov_b32_e32 v96, v2
	v_mov_b32_e32 v97, v2
	v_mov_b32_e32 v106, v2
	v_mov_b32_e32 v107, v2
	v_mov_b32_e32 v108, v2
	v_mov_b32_e32 v109, v2
	v_mov_b32_e32 v110, v2
	v_mov_b32_e32 v111, v2
	v_mov_b32_e32 v112, v2
	v_mov_b32_e32 v113, v2
	v_mov_b32_e32 v122, v2
	v_mov_b32_e32 v123, v2
	v_mov_b32_e32 v124, v2
	v_mov_b32_e32 v125, v2
	v_mov_b32_e32 v126, v2
	v_mov_b32_e32 v127, v2
	v_mov_b32_e32 v128, v2
	v_mov_b32_e32 v129, v2
	s_and_b64 vcc, exec, s[6:7]
	s_cbranch_vccz .Lsp_p1
	s_setprio 1
.Lsp_p1:
	s_branch .LBB0_277
.Lkback_277:
	v_lshl_add_u64 v[244:245], v[218:219], 0, s[8:9]
	s_mov_b32 m0, s44
	s_nop 0
	global_load_lds_dwordx4 v[244:245], off
	v_lshl_add_u64 v[244:245], v[220:221], 0, s[8:9]
	s_mov_b32 m0, s45
	s_nop 0
	global_load_lds_dwordx4 v[244:245], off
.LBB0_277:
	ds_read_b128 v[148:151], v145
	ds_read_b128 v[152:155], v145 offset:1024
	ds_read_b128 v[156:159], v145 offset:2048
	ds_read_b128 v[160:163], v145 offset:3072
	ds_read_b128 v[166:169], v146
	ds_read_b128 v[170:173], v146 offset:1024
	ds_read_b128 v[174:177], v146 offset:2048
	ds_read_b128 v[178:181], v146 offset:3072
	s_add_u32 s28, s26, 0xfff80080
	s_addc_u32 s29, s27, -1
	s_cmp_eq_u32 s50, 28
	s_cselect_b32 s31, s2, s29
	s_cselect_b32 s30, s13, s28
	s_cselect_b32 s29, s15, s33
	s_cselect_b32 s28, s23, s25
	v_lshl_add_u64 v[214:215], s[26:27], 0, v[138:139]
	s_add_i32 m0, s37, 0xc000
	ds_read_b128 v[182:185], v147
	ds_read_b128 v[186:189], v147 offset:1024
	ds_read_b128 v[190:193], v147 offset:2048
	ds_read_b128 v[194:197], v147 offset:3072
	ds_read_b128 v[198:201], v147 offset:4096
	ds_read_b128 v[202:205], v147 offset:5120
	ds_read_b128 v[206:209], v147 offset:6144
	ds_read_b128 v[210:213], v147 offset:7168
	global_load_lds_dwordx4 v[214:215], off
	v_lshl_add_u64 v[214:215], s[26:27], 0, v[140:141]
	s_add_i32 m0, s37, 0xe000
	s_nop 0
	global_load_lds_dwordx4 v[214:215], off
	s_waitcnt vmcnt(8)
	s_waitcnt lgkmcnt(0)
	s_barrier
	v_mfma_f32_16x16x32_bf16 v[126:129], v[148:151], v[182:185], v[126:129]
	v_mfma_f32_16x16x32_bf16 v[122:125], v[156:159], v[182:185], v[122:125]
	v_mfma_f32_16x16x32_bf16 v[110:113], v[148:151], v[190:193], v[110:113]
	v_mfma_f32_16x16x32_bf16 v[106:109], v[156:159], v[190:193], v[106:109]
	v_mfma_f32_16x16x32_bf16 v[94:97], v[148:151], v[198:201], v[94:97]
	v_mfma_f32_16x16x32_bf16 v[90:93], v[156:159], v[198:201], v[90:93]
	v_mfma_f32_16x16x32_bf16 v[78:81], v[148:151], v[206:209], v[78:81]
	v_mfma_f32_16x16x32_bf16 v[74:77], v[156:159], v[206:209], v[74:77]
	v_mfma_f32_16x16x32_bf16 v[126:129], v[152:155], v[186:189], v[126:129]
	v_mfma_f32_16x16x32_bf16 v[122:125], v[160:163], v[186:189], v[122:125]
	v_mfma_f32_16x16x32_bf16 v[110:113], v[152:155], v[194:197], v[110:113]
	v_mfma_f32_16x16x32_bf16 v[106:109], v[160:163], v[194:197], v[106:109]
	v_mfma_f32_16x16x32_bf16 v[94:97], v[152:155], v[202:205], v[94:97]
	v_mfma_f32_16x16x32_bf16 v[90:93], v[160:163], v[202:205], v[90:93]
	v_mfma_f32_16x16x32_bf16 v[78:81], v[152:155], v[210:213], v[78:81]
	v_mfma_f32_16x16x32_bf16 v[74:77], v[160:163], v[210:213], v[74:77]
	v_mfma_f32_16x16x32_bf16 v[118:121], v[166:169], v[182:185], v[118:121]
	v_mfma_f32_16x16x32_bf16 v[114:117], v[174:177], v[182:185], v[114:117]
	v_mfma_f32_16x16x32_bf16 v[102:105], v[166:169], v[190:193], v[102:105]
	v_mfma_f32_16x16x32_bf16 v[98:101], v[174:177], v[190:193], v[98:101]
	v_mfma_f32_16x16x32_bf16 v[86:89], v[166:169], v[198:201], v[86:89]
	v_mfma_f32_16x16x32_bf16 v[82:85], v[174:177], v[198:201], v[82:85]
	v_mfma_f32_16x16x32_bf16 v[70:73], v[166:169], v[206:209], v[70:73]
	v_mfma_f32_16x16x32_bf16 v[66:69], v[174:177], v[206:209], v[66:69]
	v_mfma_f32_16x16x32_bf16 v[118:121], v[170:173], v[186:189], v[118:121]
	v_mfma_f32_16x16x32_bf16 v[114:117], v[178:181], v[186:189], v[114:117]
	v_mfma_f32_16x16x32_bf16 v[102:105], v[170:173], v[194:197], v[102:105]
	v_mfma_f32_16x16x32_bf16 v[98:101], v[178:181], v[194:197], v[98:101]
	v_mfma_f32_16x16x32_bf16 v[86:89], v[170:173], v[202:205], v[86:89]
	v_mfma_f32_16x16x32_bf16 v[82:85], v[178:181], v[202:205], v[82:85]
	v_mfma_f32_16x16x32_bf16 v[70:73], v[170:173], v[210:213], v[70:73]
	v_mfma_f32_16x16x32_bf16 v[66:69], v[178:181], v[210:213], v[66:69]
	s_barrier
	s_add_i32 s51, s48, s36
	v_lshl_add_u64 v[214:215], s[28:29], 0, v[132:133]
	s_mov_b32 m0, s51
	ds_read_b128 v[182:185], v147 offset:16384
	ds_read_b128 v[186:189], v147 offset:17408
	ds_read_b128 v[190:193], v147 offset:18432
	ds_read_b128 v[194:197], v147 offset:19456
	ds_read_b128 v[198:201], v147 offset:20480
	ds_read_b128 v[202:205], v147 offset:21504
	ds_read_b128 v[206:209], v147 offset:22528
	ds_read_b128 v[210:213], v147 offset:23552
	global_load_lds_dwordx4 v[214:215], off
	s_add_i32 m0, s51, 0x2000
	s_add_u32 s52, s28, 0x80000
	v_lshl_add_u64 v[216:217], s[28:29], 0, v[136:137]
	s_addc_u32 s53, s29, 0
	s_add_i32 s51, s49, s36
	global_load_lds_dwordx4 v[216:217], off
	v_lshl_add_u64 v[218:219], s[52:53], 0, v[132:133]
	s_mov_b32 m0, s51
	v_lshl_add_u64 v[220:221], s[30:31], 0, v[134:135]
	global_load_lds_dwordx4 v[218:219], off
	v_lshl_add_u64 v[218:219], s[52:53], 0, v[136:137]
	s_add_i32 m0, s51, 0x2000
	s_nop 0
	global_load_lds_dwordx4 v[218:219], off
	v_lshl_add_u64 v[218:219], s[30:31], 0, v[130:131]
	s_waitcnt vmcnt(6)
	s_waitcnt lgkmcnt(0)
	s_barrier
	v_mfma_f32_16x16x32_bf16 v[62:65], v[148:151], v[182:185], v[62:65]
	v_mfma_f32_16x16x32_bf16 v[58:61], v[156:159], v[182:185], v[58:61]
	v_mfma_f32_16x16x32_bf16 v[46:49], v[148:151], v[190:193], v[46:49]
	v_mfma_f32_16x16x32_bf16 v[42:45], v[156:159], v[190:193], v[42:45]
	v_mfma_f32_16x16x32_bf16 v[30:33], v[148:151], v[198:201], v[30:33]
	v_mfma_f32_16x16x32_bf16 v[26:29], v[156:159], v[198:201], v[26:29]
	v_mfma_f32_16x16x32_bf16 v[14:17], v[148:151], v[206:209], v[14:17]
	v_mfma_f32_16x16x32_bf16 v[10:13], v[156:159], v[206:209], v[10:13]
	v_mfma_f32_16x16x32_bf16 v[62:65], v[152:155], v[186:189], v[62:65]
	v_mfma_f32_16x16x32_bf16 v[58:61], v[160:163], v[186:189], v[58:61]
	v_mfma_f32_16x16x32_bf16 v[46:49], v[152:155], v[194:197], v[46:49]
	v_mfma_f32_16x16x32_bf16 v[42:45], v[160:163], v[194:197], v[42:45]
	v_mfma_f32_16x16x32_bf16 v[30:33], v[152:155], v[202:205], v[30:33]
	v_mfma_f32_16x16x32_bf16 v[26:29], v[160:163], v[202:205], v[26:29]
	v_mfma_f32_16x16x32_bf16 v[14:17], v[152:155], v[210:213], v[14:17]
	v_mfma_f32_16x16x32_bf16 v[10:13], v[160:163], v[210:213], v[10:13]
	v_mfma_f32_16x16x32_bf16 v[54:57], v[166:169], v[182:185], v[54:57]
	v_mfma_f32_16x16x32_bf16 v[50:53], v[174:177], v[182:185], v[50:53]
	v_mfma_f32_16x16x32_bf16 v[38:41], v[166:169], v[190:193], v[38:41]
	v_mfma_f32_16x16x32_bf16 v[34:37], v[174:177], v[190:193], v[34:37]
	v_mfma_f32_16x16x32_bf16 v[22:25], v[166:169], v[198:201], v[22:25]
	v_mfma_f32_16x16x32_bf16 v[18:21], v[174:177], v[198:201], v[18:21]
	v_mfma_f32_16x16x32_bf16 v[6:9], v[166:169], v[206:209], v[6:9]
	v_mfma_f32_16x16x32_bf16 v[2:5], v[174:177], v[206:209], v[2:5]
	v_mfma_f32_16x16x32_bf16 v[54:57], v[170:173], v[186:189], v[54:57]
	v_mfma_f32_16x16x32_bf16 v[50:53], v[178:181], v[186:189], v[50:53]
	v_mfma_f32_16x16x32_bf16 v[38:41], v[170:173], v[194:197], v[38:41]
	v_mfma_f32_16x16x32_bf16 v[34:37], v[178:181], v[194:197], v[34:37]
	v_mfma_f32_16x16x32_bf16 v[22:25], v[170:173], v[202:205], v[22:25]
	v_mfma_f32_16x16x32_bf16 v[18:21], v[178:181], v[202:205], v[18:21]
	v_mfma_f32_16x16x32_bf16 v[6:9], v[170:173], v[210:213], v[6:9]
	v_mfma_f32_16x16x32_bf16 v[2:5], v[178:181], v[210:213], v[2:5]
	s_barrier
	s_mov_b32 m0, s37
	s_nop 0
	global_load_lds_dwordx4 v[218:219], off
	s_mov_b32 m0, s38
	s_nop 0
	global_load_lds_dwordx4 v[220:221], off
	s_add_i32 s51, 0, 0x18000
	s_add_i32 s52, 0, 0x1c000
	v_add_u32_e32 v160, s51, v144
	v_add_u32_e32 v164, s52, v144
	ds_read_b128 v[148:151], v160
	ds_read_b128 v[152:155], v160 offset:1024
	ds_read_b128 v[156:159], v160 offset:2048
	ds_read_b128 v[160:163], v160 offset:3072
	ds_read_b128 v[166:169], v164
	ds_read_b128 v[170:173], v164 offset:1024
	ds_read_b128 v[174:177], v164 offset:2048
	ds_read_b128 v[178:181], v164 offset:3072
	s_add_u32 s30, s30, 0x80000
	s_addc_u32 s31, s31, 0
	s_mov_b32 m0, s39
	v_lshl_add_u64 v[222:223], s[30:31], 0, v[130:131]
	ds_read_b128 v[182:185], v147 offset:32768
	ds_read_b128 v[186:189], v147 offset:33792
	ds_read_b128 v[190:193], v147 offset:34816
	ds_read_b128 v[194:197], v147 offset:35840
	ds_read_b128 v[198:201], v147 offset:36864
	ds_read_b128 v[202:205], v147 offset:37888
	ds_read_b128 v[206:209], v147 offset:38912
	ds_read_b128 v[210:213], v147 offset:39936
	global_load_lds_dwordx4 v[222:223], off
	v_lshl_add_u64 v[222:223], s[30:31], 0, v[134:135]
	s_mov_b32 m0, s40
	s_nop 0
	global_load_lds_dwordx4 v[222:223], off
	s_waitcnt vmcnt(8)
	s_waitcnt lgkmcnt(0)
	s_barrier
	v_mfma_f32_16x16x32_bf16 v[126:129], v[148:151], v[182:185], v[126:129]
	v_mfma_f32_16x16x32_bf16 v[122:125], v[156:159], v[182:185], v[122:125]
	v_mfma_f32_16x16x32_bf16 v[110:113], v[148:151], v[190:193], v[110:113]
	v_mfma_f32_16x16x32_bf16 v[106:109], v[156:159], v[190:193], v[106:109]
	v_mfma_f32_16x16x32_bf16 v[94:97], v[148:151], v[198:201], v[94:97]
	v_mfma_f32_16x16x32_bf16 v[90:93], v[156:159], v[198:201], v[90:93]
	v_mfma_f32_16x16x32_bf16 v[78:81], v[148:151], v[206:209], v[78:81]
	v_mfma_f32_16x16x32_bf16 v[74:77], v[156:159], v[206:209], v[74:77]
	v_mfma_f32_16x16x32_bf16 v[126:129], v[152:155], v[186:189], v[126:129]
	v_mfma_f32_16x16x32_bf16 v[122:125], v[160:163], v[186:189], v[122:125]
	v_mfma_f32_16x16x32_bf16 v[110:113], v[152:155], v[194:197], v[110:113]
	v_mfma_f32_16x16x32_bf16 v[106:109], v[160:163], v[194:197], v[106:109]
	v_mfma_f32_16x16x32_bf16 v[94:97], v[152:155], v[202:205], v[94:97]
	v_mfma_f32_16x16x32_bf16 v[90:93], v[160:163], v[202:205], v[90:93]
	v_mfma_f32_16x16x32_bf16 v[78:81], v[152:155], v[210:213], v[78:81]
	v_mfma_f32_16x16x32_bf16 v[74:77], v[160:163], v[210:213], v[74:77]
	v_mfma_f32_16x16x32_bf16 v[118:121], v[166:169], v[182:185], v[118:121]
	v_mfma_f32_16x16x32_bf16 v[114:117], v[174:177], v[182:185], v[114:117]
	v_mfma_f32_16x16x32_bf16 v[102:105], v[166:169], v[190:193], v[102:105]
	v_mfma_f32_16x16x32_bf16 v[98:101], v[174:177], v[190:193], v[98:101]
	v_mfma_f32_16x16x32_bf16 v[86:89], v[166:169], v[198:201], v[86:89]
	v_mfma_f32_16x16x32_bf16 v[82:85], v[174:177], v[198:201], v[82:85]
	v_mfma_f32_16x16x32_bf16 v[70:73], v[166:169], v[206:209], v[70:73]
	v_mfma_f32_16x16x32_bf16 v[66:69], v[174:177], v[206:209], v[66:69]
	v_mfma_f32_16x16x32_bf16 v[118:121], v[170:173], v[186:189], v[118:121]
	v_mfma_f32_16x16x32_bf16 v[114:117], v[178:181], v[186:189], v[114:117]
	v_mfma_f32_16x16x32_bf16 v[102:105], v[170:173], v[194:197], v[102:105]
	v_mfma_f32_16x16x32_bf16 v[98:101], v[178:181], v[194:197], v[98:101]
	v_mfma_f32_16x16x32_bf16 v[86:89], v[170:173], v[202:205], v[86:89]
	v_mfma_f32_16x16x32_bf16 v[82:85], v[178:181], v[202:205], v[82:85]
	v_mfma_f32_16x16x32_bf16 v[70:73], v[170:173], v[210:213], v[70:73]
	v_mfma_f32_16x16x32_bf16 v[66:69], v[178:181], v[210:213], v[66:69]
	s_barrier
	s_add_i32 s30, s51, s36
	v_lshl_add_u64 v[214:215], v[214:215], 0, s[8:9]
	s_mov_b32 m0, s30
	ds_read_b128 v[182:185], v147 offset:49152
	ds_read_b128 v[186:189], v147 offset:50176
	ds_read_b128 v[190:193], v147 offset:51200
	ds_read_b128 v[194:197], v147 offset:52224
	ds_read_b128 v[198:201], v147 offset:53248
	ds_read_b128 v[202:205], v147 offset:54272
	ds_read_b128 v[206:209], v147 offset:55296
	ds_read_b128 v[210:213], v147 offset:56320
	global_load_lds_dwordx4 v[214:215], off
	s_add_i32 m0, s30, 0x2000
	s_add_u32 s28, s28, 0x80080
	v_lshl_add_u64 v[214:215], v[216:217], 0, s[8:9]
	s_addc_u32 s29, s29, 0
	s_add_i32 s30, s52, s36
	global_load_lds_dwordx4 v[214:215], off
	v_lshl_add_u64 v[214:215], s[28:29], 0, v[132:133]
	s_mov_b32 m0, s30
	s_nop 0
	global_load_lds_dwordx4 v[214:215], off
	v_lshl_add_u64 v[214:215], s[28:29], 0, v[136:137]
	s_add_i32 m0, s30, 0x2000
	s_nop 0
	global_load_lds_dwordx4 v[214:215], off
	s_waitcnt vmcnt(6)
	s_waitcnt lgkmcnt(0)
	s_barrier
	v_mfma_f32_16x16x32_bf16 v[62:65], v[148:151], v[182:185], v[62:65]
	v_mfma_f32_16x16x32_bf16 v[58:61], v[156:159], v[182:185], v[58:61]
	v_mfma_f32_16x16x32_bf16 v[46:49], v[148:151], v[190:193], v[46:49]
	v_mfma_f32_16x16x32_bf16 v[42:45], v[156:159], v[190:193], v[42:45]
	v_mfma_f32_16x16x32_bf16 v[30:33], v[148:151], v[198:201], v[30:33]
	v_mfma_f32_16x16x32_bf16 v[26:29], v[156:159], v[198:201], v[26:29]
	v_mfma_f32_16x16x32_bf16 v[14:17], v[148:151], v[206:209], v[14:17]
	v_mfma_f32_16x16x32_bf16 v[10:13], v[156:159], v[206:209], v[10:13]
	v_mfma_f32_16x16x32_bf16 v[62:65], v[152:155], v[186:189], v[62:65]
	v_mfma_f32_16x16x32_bf16 v[58:61], v[160:163], v[186:189], v[58:61]
	v_mfma_f32_16x16x32_bf16 v[46:49], v[152:155], v[194:197], v[46:49]
	v_mfma_f32_16x16x32_bf16 v[42:45], v[160:163], v[194:197], v[42:45]
	v_mfma_f32_16x16x32_bf16 v[30:33], v[152:155], v[202:205], v[30:33]
	v_mfma_f32_16x16x32_bf16 v[26:29], v[160:163], v[202:205], v[26:29]
	v_mfma_f32_16x16x32_bf16 v[14:17], v[152:155], v[210:213], v[14:17]
	v_mfma_f32_16x16x32_bf16 v[10:13], v[160:163], v[210:213], v[10:13]
	v_mfma_f32_16x16x32_bf16 v[54:57], v[166:169], v[182:185], v[54:57]
	v_mfma_f32_16x16x32_bf16 v[50:53], v[174:177], v[182:185], v[50:53]
	v_mfma_f32_16x16x32_bf16 v[38:41], v[166:169], v[190:193], v[38:41]
	v_mfma_f32_16x16x32_bf16 v[34:37], v[174:177], v[190:193], v[34:37]
	v_mfma_f32_16x16x32_bf16 v[22:25], v[166:169], v[198:201], v[22:25]
	v_mfma_f32_16x16x32_bf16 v[18:21], v[174:177], v[198:201], v[18:21]
	v_mfma_f32_16x16x32_bf16 v[6:9], v[166:169], v[206:209], v[6:9]
	v_mfma_f32_16x16x32_bf16 v[2:5], v[174:177], v[206:209], v[2:5]
	v_mfma_f32_16x16x32_bf16 v[54:57], v[170:173], v[186:189], v[54:57]
	v_mfma_f32_16x16x32_bf16 v[50:53], v[178:181], v[186:189], v[50:53]
	v_mfma_f32_16x16x32_bf16 v[38:41], v[170:173], v[194:197], v[38:41]
	v_mfma_f32_16x16x32_bf16 v[34:37], v[178:181], v[194:197], v[34:37]
	v_mfma_f32_16x16x32_bf16 v[22:25], v[170:173], v[202:205], v[22:25]
	v_mfma_f32_16x16x32_bf16 v[18:21], v[178:181], v[202:205], v[18:21]
	v_mfma_f32_16x16x32_bf16 v[6:9], v[170:173], v[210:213], v[6:9]
	v_mfma_f32_16x16x32_bf16 v[2:5], v[178:181], v[210:213], v[2:5]
	s_barrier
	s_add_i32 s50, s50, 2
	s_add_u32 s26, s26, 0x100
	s_addc_u32 s27, s27, 0
	s_add_u32 s25, s25, 0x100
	s_addc_u32 s33, s33, 0
	s_cmp_gt_u32 s50, 29
	s_cbranch_scc0 .Lkback_277
	v_lshl_add_u64 v[244:245], v[218:219], 0, s[8:9]
	s_mov_b32 m0, s44
	s_nop 0
	global_load_lds_dwordx4 v[244:245], off
	v_lshl_add_u64 v[244:245], v[220:221], 0, s[8:9]
	s_mov_b32 m0, s45
	s_nop 0
	global_load_lds_dwordx4 v[244:245], off
	s_setprio 0
	s_and_b64 vcc, exec, s[10:11]
	s_cbranch_vccz .LBB0_280
	s_barrier

.LBB0_703:
	s_add_u32 s22, s22, 0x80080
	s_addc_u32 s23, s23, 0
	s_add_u32 s5, s24, 0x100
	v_mov_b32_e32 v2, 0
	s_addc_u32 s15, s25, 0
	s_mov_b32 s45, -2
	v_mov_b32_e32 v3, v2
	v_mov_b32_e32 v4, v2
	v_mov_b32_e32 v5, v2
	v_mov_b32_e32 v6, v2
	v_mov_b32_e32 v7, v2
	v_mov_b32_e32 v8, v2
	v_mov_b32_e32 v9, v2
	v_mov_b32_e32 v18, v2
	v_mov_b32_e32 v19, v2
	v_mov_b32_e32 v20, v2
	v_mov_b32_e32 v21, v2
	v_mov_b32_e32 v22, v2
	v_mov_b32_e32 v23, v2
	v_mov_b32_e32 v24, v2
	v_mov_b32_e32 v25, v2
	v_mov_b32_e32 v34, v2
	v_mov_b32_e32 v35, v2
	v_mov_b32_e32 v36, v2
	v_mov_b32_e32 v37, v2
	v_mov_b32_e32 v38, v2
	v_mov_b32_e32 v39, v2
	v_mov_b32_e32 v40, v2
	v_mov_b32_e32 v41, v2
	v_mov_b32_e32 v50, v2
	v_mov_b32_e32 v51, v2
	v_mov_b32_e32 v52, v2
	v_mov_b32_e32 v53, v2
	v_mov_b32_e32 v54, v2
	v_mov_b32_e32 v55, v2
	v_mov_b32_e32 v56, v2
	v_mov_b32_e32 v57, v2
	v_mov_b32_e32 v10, v2
	v_mov_b32_e32 v11, v2
	v_mov_b32_e32 v12, v2
	v_mov_b32_e32 v13, v2
	v_mov_b32_e32 v14, v2
	v_mov_b32_e32 v15, v2
	v_mov_b32_e32 v16, v2
	v_mov_b32_e32 v17, v2
	v_mov_b32_e32 v26, v2
	v_mov_b32_e32 v27, v2
	v_mov_b32_e32 v28, v2
	v_mov_b32_e32 v29, v2
	v_mov_b32_e32 v30, v2
	v_mov_b32_e32 v31, v2
	v_mov_b32_e32 v32, v2
	v_mov_b32_e32 v33, v2
	v_mov_b32_e32 v42, v2
	v_mov_b32_e32 v43, v2
	v_mov_b32_e32 v44, v2
	v_mov_b32_e32 v45, v2
	v_mov_b32_e32 v46, v2
	v_mov_b32_e32 v47, v2
	v_mov_b32_e32 v48, v2
	v_mov_b32_e32 v49, v2
	v_mov_b32_e32 v58, v2
	v_mov_b32_e32 v59, v2
	v_mov_b32_e32 v60, v2
	v_mov_b32_e32 v61, v2
	v_mov_b32_e32 v62, v2
	v_mov_b32_e32 v63, v2
	v_mov_b32_e32 v64, v2
	v_mov_b32_e32 v65, v2
	v_mov_b32_e32 v66, v2
	v_mov_b32_e32 v67, v2
	v_mov_b32_e32 v68, v2
	v_mov_b32_e32 v69, v2
	v_mov_b32_e32 v70, v2
	v_mov_b32_e32 v71, v2
	v_mov_b32_e32 v72, v2
	v_mov_b32_e32 v73, v2
	v_mov_b32_e32 v82, v2
	v_mov_b32_e32 v83, v2
	v_mov_b32_e32 v84, v2
	v_mov_b32_e32 v85, v2
	v_mov_b32_e32 v86, v2
	v_mov_b32_e32 v87, v2
	v_mov_b32_e32 v88, v2
	v_mov_b32_e32 v89, v2
	v_mov_b32_e32 v98, v2
	v_mov_b32_e32 v99, v2
	v_mov_b32_e32 v100, v2
	v_mov_b32_e32 v101, v2
	v_mov_b32_e32 v102, v2
	v_mov_b32_e32 v103, v2
	v_mov_b32_e32 v104, v2
	v_mov_b32_e32 v105, v2
	v_mov_b32_e32 v114, v2
	v_mov_b32_e32 v115, v2
	v_mov_b32_e32 v116, v2
	v_mov_b32_e32 v117, v2
	v_mov_b32_e32 v118, v2
	v_mov_b32_e32 v119, v2
	v_mov_b32_e32 v120, v2
	v_mov_b32_e32 v121, v2
	v_mov_b32_e32 v74, v2
	v_mov_b32_e32 v75, v2
	v_mov_b32_e32 v76, v2
	v_mov_b32_e32 v77, v2
	v_mov_b32_e32 v78, v2
	v_mov_b32_e32 v79, v2
	v_mov_b32_e32 v80, v2
	v_mov_b32_e32 v81, v2
	v_mov_b32_e32 v90, v2
	v_mov_b32_e32 v91, v2
	v_mov_b32_e32 v92, v2
	v_mov_b32_e32 v93, v2
	v_mov_b32_e32 v94, v2
	v_mov_b32_e32 v95, v2
	v_mov_b32_e32 v96, v2
	v_mov_b32_e32 v97, v2
	v_mov_b32_e32 v106, v2
	v_mov_b32_e32 v107, v2
	v_mov_b32_e32 v108, v2
	v_mov_b32_e32 v109, v2
	v_mov_b32_e32 v110, v2
	v_mov_b32_e32 v111, v2
	v_mov_b32_e32 v112, v2
	v_mov_b32_e32 v113, v2
	v_mov_b32_e32 v122, v2
	v_mov_b32_e32 v123, v2
	v_mov_b32_e32 v124, v2
	v_mov_b32_e32 v125, v2
	v_mov_b32_e32 v126, v2
	v_mov_b32_e32 v127, v2
	v_mov_b32_e32 v128, v2
	v_mov_b32_e32 v129, v2
	s_and_b64 s[98:99], exec, s[12:13]
	s_cbranch_scc1 .Lsp_p4
	s_setprio 1
.Lsp_p4:
	s_branch .LBB0_704
.Lkback_704:
	v_lshl_add_u64 v[244:245], v[222:223], 0, s[10:11]
	s_mov_b32 m0, s38
	s_nop 0
	global_load_lds_dwordx4 v[244:245], off
	v_lshl_add_u64 v[244:245], v[224:225], 0, s[10:11]
	s_mov_b32 m0, s39
	s_nop 0
	global_load_lds_dwordx4 v[244:245], off
.LBB0_704:
	ds_read_b128 v[144:147], v152
	ds_read_b128 v[156:159], v152 offset:1024
	ds_read_b128 v[160:163], v152 offset:2048
	ds_read_b128 v[166:169], v152 offset:3072
	ds_read_b128 v[170:173], v153
	ds_read_b128 v[174:177], v153 offset:1024
	ds_read_b128 v[178:181], v153 offset:2048
	ds_read_b128 v[182:185], v153 offset:3072
	s_add_u32 s24, s22, 0xfff80080
	s_addc_u32 s25, s23, -1
	s_cmp_eq_u32 s45, 28
	s_cselect_b32 s27, s17, s25
	s_cselect_b32 s26, s16, s24
	s_cselect_b32 s25, s21, s15
	s_cselect_b32 s24, s20, s5
	s_mov_b32 m0, s42
	v_lshl_add_u64 v[218:219], s[22:23], 0, v[140:141]
	ds_read_b128 v[186:189], v154
	ds_read_b128 v[190:193], v154 offset:1024
	ds_read_b128 v[194:197], v154 offset:2048
	ds_read_b128 v[198:201], v154 offset:3072
	ds_read_b128 v[202:205], v154 offset:4096
	ds_read_b128 v[206:209], v154 offset:5120
	ds_read_b128 v[210:213], v154 offset:6144
	ds_read_b128 v[214:217], v154 offset:7168
	global_load_lds_dwordx4 v[218:219], off
	v_lshl_add_u64 v[218:219], s[22:23], 0, v[142:143]
	s_add_i32 m0, s30, 0xe000
	s_nop 0
	global_load_lds_dwordx4 v[218:219], off
	s_waitcnt vmcnt(8)
	s_waitcnt lgkmcnt(0)
	s_barrier
	v_mfma_f32_16x16x32_bf16 v[126:129], v[144:147], v[186:189], v[126:129]
	v_mfma_f32_16x16x32_bf16 v[122:125], v[160:163], v[186:189], v[122:125]
	v_mfma_f32_16x16x32_bf16 v[110:113], v[144:147], v[194:197], v[110:113]
	v_mfma_f32_16x16x32_bf16 v[106:109], v[160:163], v[194:197], v[106:109]
	v_mfma_f32_16x16x32_bf16 v[94:97], v[144:147], v[202:205], v[94:97]
	v_mfma_f32_16x16x32_bf16 v[90:93], v[160:163], v[202:205], v[90:93]
	v_mfma_f32_16x16x32_bf16 v[78:81], v[144:147], v[210:213], v[78:81]
	v_mfma_f32_16x16x32_bf16 v[74:77], v[160:163], v[210:213], v[74:77]
	v_mfma_f32_16x16x32_bf16 v[126:129], v[156:159], v[190:193], v[126:129]
	v_mfma_f32_16x16x32_bf16 v[122:125], v[166:169], v[190:193], v[122:125]
	v_mfma_f32_16x16x32_bf16 v[110:113], v[156:159], v[198:201], v[110:113]
	v_mfma_f32_16x16x32_bf16 v[106:109], v[166:169], v[198:201], v[106:109]
	v_mfma_f32_16x16x32_bf16 v[94:97], v[156:159], v[206:209], v[94:97]
	v_mfma_f32_16x16x32_bf16 v[90:93], v[166:169], v[206:209], v[90:93]
	v_mfma_f32_16x16x32_bf16 v[78:81], v[156:159], v[214:217], v[78:81]
	v_mfma_f32_16x16x32_bf16 v[74:77], v[166:169], v[214:217], v[74:77]
	v_mfma_f32_16x16x32_bf16 v[118:121], v[170:173], v[186:189], v[118:121]
	v_mfma_f32_16x16x32_bf16 v[114:117], v[178:181], v[186:189], v[114:117]
	v_mfma_f32_16x16x32_bf16 v[102:105], v[170:173], v[194:197], v[102:105]
	v_mfma_f32_16x16x32_bf16 v[98:101], v[178:181], v[194:197], v[98:101]
	v_mfma_f32_16x16x32_bf16 v[86:89], v[170:173], v[202:205], v[86:89]
	v_mfma_f32_16x16x32_bf16 v[82:85], v[178:181], v[202:205], v[82:85]
	v_mfma_f32_16x16x32_bf16 v[70:73], v[170:173], v[210:213], v[70:73]
	v_mfma_f32_16x16x32_bf16 v[66:69], v[178:181], v[210:213], v[66:69]
	v_mfma_f32_16x16x32_bf16 v[118:121], v[174:177], v[190:193], v[118:121]
	v_mfma_f32_16x16x32_bf16 v[114:117], v[182:185], v[190:193], v[114:117]
	v_mfma_f32_16x16x32_bf16 v[102:105], v[174:177], v[198:201], v[102:105]
	v_mfma_f32_16x16x32_bf16 v[98:101], v[182:185], v[198:201], v[98:101]
	v_mfma_f32_16x16x32_bf16 v[86:89], v[174:177], v[206:209], v[86:89]
	v_mfma_f32_16x16x32_bf16 v[82:85], v[182:185], v[206:209], v[82:85]
	v_mfma_f32_16x16x32_bf16 v[70:73], v[174:177], v[214:217], v[70:73]
	v_mfma_f32_16x16x32_bf16 v[66:69], v[182:185], v[214:217], v[66:69]
	s_barrier
	s_add_i32 s46, s40, s29
	v_lshl_add_u64 v[218:219], s[24:25], 0, v[134:135]
	s_mov_b32 m0, s46
	ds_read_b128 v[186:189], v154 offset:16384
	ds_read_b128 v[190:193], v154 offset:17408
	ds_read_b128 v[194:197], v154 offset:18432
	ds_read_b128 v[198:201], v154 offset:19456
	ds_read_b128 v[202:205], v154 offset:20480
	ds_read_b128 v[206:209], v154 offset:21504
	ds_read_b128 v[210:213], v154 offset:22528
	ds_read_b128 v[214:217], v154 offset:23552
	global_load_lds_dwordx4 v[218:219], off
	s_add_i32 m0, s46, 0x2000
	s_add_u32 s46, s24, 0x80000
	v_lshl_add_u64 v[220:221], s[24:25], 0, v[138:139]
	s_addc_u32 s47, s25, 0
	s_add_i32 s48, s41, s29
	global_load_lds_dwordx4 v[220:221], off
	v_lshl_add_u64 v[222:223], s[46:47], 0, v[134:135]
	s_mov_b32 m0, s48
	v_lshl_add_u64 v[224:225], s[26:27], 0, v[136:137]
	global_load_lds_dwordx4 v[222:223], off
	v_lshl_add_u64 v[222:223], s[46:47], 0, v[138:139]
	s_add_i32 m0, s48, 0x2000
	s_nop 0
	global_load_lds_dwordx4 v[222:223], off
	v_lshl_add_u64 v[222:223], s[26:27], 0, v[132:133]
	s_waitcnt vmcnt(6)
	s_waitcnt lgkmcnt(0)
	s_barrier
	v_mfma_f32_16x16x32_bf16 v[62:65], v[144:147], v[186:189], v[62:65]
	v_mfma_f32_16x16x32_bf16 v[58:61], v[160:163], v[186:189], v[58:61]
	v_mfma_f32_16x16x32_bf16 v[46:49], v[144:147], v[194:197], v[46:49]
	v_mfma_f32_16x16x32_bf16 v[42:45], v[160:163], v[194:197], v[42:45]
	v_mfma_f32_16x16x32_bf16 v[30:33], v[144:147], v[202:205], v[30:33]
	v_mfma_f32_16x16x32_bf16 v[26:29], v[160:163], v[202:205], v[26:29]
	v_mfma_f32_16x16x32_bf16 v[14:17], v[144:147], v[210:213], v[14:17]
	v_mfma_f32_16x16x32_bf16 v[10:13], v[160:163], v[210:213], v[10:13]
	v_mfma_f32_16x16x32_bf16 v[62:65], v[156:159], v[190:193], v[62:65]
	v_mfma_f32_16x16x32_bf16 v[58:61], v[166:169], v[190:193], v[58:61]
	v_mfma_f32_16x16x32_bf16 v[46:49], v[156:159], v[198:201], v[46:49]
	v_mfma_f32_16x16x32_bf16 v[42:45], v[166:169], v[198:201], v[42:45]
	v_mfma_f32_16x16x32_bf16 v[30:33], v[156:159], v[206:209], v[30:33]
	v_mfma_f32_16x16x32_bf16 v[26:29], v[166:169], v[206:209], v[26:29]
	v_mfma_f32_16x16x32_bf16 v[14:17], v[156:159], v[214:217], v[14:17]
	v_mfma_f32_16x16x32_bf16 v[10:13], v[166:169], v[214:217], v[10:13]
	v_mfma_f32_16x16x32_bf16 v[54:57], v[170:173], v[186:189], v[54:57]
	v_mfma_f32_16x16x32_bf16 v[50:53], v[178:181], v[186:189], v[50:53]
	v_mfma_f32_16x16x32_bf16 v[38:41], v[170:173], v[194:197], v[38:41]
	v_mfma_f32_16x16x32_bf16 v[34:37], v[178:181], v[194:197], v[34:37]
	v_mfma_f32_16x16x32_bf16 v[22:25], v[170:173], v[202:205], v[22:25]
	v_mfma_f32_16x16x32_bf16 v[18:21], v[178:181], v[202:205], v[18:21]
	v_mfma_f32_16x16x32_bf16 v[6:9], v[170:173], v[210:213], v[6:9]
	v_mfma_f32_16x16x32_bf16 v[2:5], v[178:181], v[210:213], v[2:5]
	v_mfma_f32_16x16x32_bf16 v[54:57], v[174:177], v[190:193], v[54:57]
	v_mfma_f32_16x16x32_bf16 v[50:53], v[182:185], v[190:193], v[50:53]
	v_mfma_f32_16x16x32_bf16 v[38:41], v[174:177], v[198:201], v[38:41]
	v_mfma_f32_16x16x32_bf16 v[34:37], v[182:185], v[198:201], v[34:37]
	v_mfma_f32_16x16x32_bf16 v[22:25], v[174:177], v[206:209], v[22:25]
	v_mfma_f32_16x16x32_bf16 v[18:21], v[182:185], v[206:209], v[18:21]
	v_mfma_f32_16x16x32_bf16 v[6:9], v[174:177], v[214:217], v[6:9]
	v_mfma_f32_16x16x32_bf16 v[2:5], v[182:185], v[214:217], v[2:5]
	s_barrier
	s_mov_b32 m0, s30
	s_nop 0
	global_load_lds_dwordx4 v[222:223], off
	s_mov_b32 m0, s31
	s_nop 0
	global_load_lds_dwordx4 v[224:225], off
	s_add_i32 s46, 0, 0x18000
	v_add_u32_e32 v155, s46, v1
	s_add_i32 s47, 0, 0x1c000
	ds_read_b128 v[144:147], v155
	ds_read_b128 v[156:159], v155 offset:1024
	ds_read_b128 v[160:163], v155 offset:2048
	ds_read_b128 v[166:169], v155 offset:3072
	v_add_u32_e32 v155, s47, v1
	ds_read_b128 v[170:173], v155
	ds_read_b128 v[174:177], v155 offset:1024
	ds_read_b128 v[178:181], v155 offset:2048
	ds_read_b128 v[182:185], v155 offset:3072
	s_add_u32 s26, s26, 0x80000
	s_addc_u32 s27, s27, 0
	s_mov_b32 m0, s33
	v_lshl_add_u64 v[226:227], s[26:27], 0, v[132:133]
	ds_read_b128 v[186:189], v154 offset:32768
	ds_read_b128 v[190:193], v154 offset:33792
	ds_read_b128 v[194:197], v154 offset:34816
	ds_read_b128 v[198:201], v154 offset:35840
	ds_read_b128 v[202:205], v154 offset:36864
	ds_read_b128 v[206:209], v154 offset:37888
	ds_read_b128 v[210:213], v154 offset:38912
	ds_read_b128 v[214:217], v154 offset:39936
	global_load_lds_dwordx4 v[226:227], off
	v_lshl_add_u64 v[226:227], s[26:27], 0, v[136:137]
	s_mov_b32 m0, s34
	s_nop 0
	global_load_lds_dwordx4 v[226:227], off
	s_waitcnt vmcnt(8)
	s_waitcnt lgkmcnt(0)
	s_barrier
	v_mfma_f32_16x16x32_bf16 v[126:129], v[144:147], v[186:189], v[126:129]
	v_mfma_f32_16x16x32_bf16 v[122:125], v[160:163], v[186:189], v[122:125]
	v_mfma_f32_16x16x32_bf16 v[110:113], v[144:147], v[194:197], v[110:113]
	v_mfma_f32_16x16x32_bf16 v[106:109], v[160:163], v[194:197], v[106:109]
	v_mfma_f32_16x16x32_bf16 v[94:97], v[144:147], v[202:205], v[94:97]
	v_mfma_f32_16x16x32_bf16 v[90:93], v[160:163], v[202:205], v[90:93]
	v_mfma_f32_16x16x32_bf16 v[78:81], v[144:147], v[210:213], v[78:81]
	v_mfma_f32_16x16x32_bf16 v[74:77], v[160:163], v[210:213], v[74:77]
	v_mfma_f32_16x16x32_bf16 v[126:129], v[156:159], v[190:193], v[126:129]
	v_mfma_f32_16x16x32_bf16 v[122:125], v[166:169], v[190:193], v[122:125]
	v_mfma_f32_16x16x32_bf16 v[110:113], v[156:159], v[198:201], v[110:113]
	v_mfma_f32_16x16x32_bf16 v[106:109], v[166:169], v[198:201], v[106:109]
	v_mfma_f32_16x16x32_bf16 v[94:97], v[156:159], v[206:209], v[94:97]
	v_mfma_f32_16x16x32_bf16 v[90:93], v[166:169], v[206:209], v[90:93]
	v_mfma_f32_16x16x32_bf16 v[78:81], v[156:159], v[214:217], v[78:81]
	v_mfma_f32_16x16x32_bf16 v[74:77], v[166:169], v[214:217], v[74:77]
	v_mfma_f32_16x16x32_bf16 v[118:121], v[170:173], v[186:189], v[118:121]
	v_mfma_f32_16x16x32_bf16 v[114:117], v[178:181], v[186:189], v[114:117]
	v_mfma_f32_16x16x32_bf16 v[102:105], v[170:173], v[194:197], v[102:105]
	v_mfma_f32_16x16x32_bf16 v[98:101], v[178:181], v[194:197], v[98:101]
	v_mfma_f32_16x16x32_bf16 v[86:89], v[170:173], v[202:205], v[86:89]
	v_mfma_f32_16x16x32_bf16 v[82:85], v[178:181], v[202:205], v[82:85]
	v_mfma_f32_16x16x32_bf16 v[70:73], v[170:173], v[210:213], v[70:73]
	v_mfma_f32_16x16x32_bf16 v[66:69], v[178:181], v[210:213], v[66:69]
	v_mfma_f32_16x16x32_bf16 v[118:121], v[174:177], v[190:193], v[118:121]
	v_mfma_f32_16x16x32_bf16 v[114:117], v[182:185], v[190:193], v[114:117]
	v_mfma_f32_16x16x32_bf16 v[102:105], v[174:177], v[198:201], v[102:105]
	v_mfma_f32_16x16x32_bf16 v[98:101], v[182:185], v[198:201], v[98:101]
	v_mfma_f32_16x16x32_bf16 v[86:89], v[174:177], v[206:209], v[86:89]
	v_mfma_f32_16x16x32_bf16 v[82:85], v[182:185], v[206:209], v[82:85]
	v_mfma_f32_16x16x32_bf16 v[70:73], v[174:177], v[214:217], v[70:73]
	v_mfma_f32_16x16x32_bf16 v[66:69], v[182:185], v[214:217], v[66:69]
	s_barrier
	s_add_i32 s26, s46, s29
	v_lshl_add_u64 v[218:219], v[218:219], 0, s[10:11]
	s_mov_b32 m0, s26
	ds_read_b128 v[186:189], v154 offset:49152
	ds_read_b128 v[190:193], v154 offset:50176
	ds_read_b128 v[194:197], v154 offset:51200
	ds_read_b128 v[198:201], v154 offset:52224
	ds_read_b128 v[202:205], v154 offset:53248
	ds_read_b128 v[206:209], v154 offset:54272
	ds_read_b128 v[210:213], v154 offset:55296
	ds_read_b128 v[214:217], v154 offset:56320
	global_load_lds_dwordx4 v[218:219], off
	s_add_i32 m0, s26, 0x2000
	s_add_u32 s24, s24, 0x80080
	v_lshl_add_u64 v[218:219], v[220:221], 0, s[10:11]
	s_addc_u32 s25, s25, 0
	s_add_i32 s26, s47, s29
	global_load_lds_dwordx4 v[218:219], off
	v_lshl_add_u64 v[218:219], s[24:25], 0, v[134:135]
	s_mov_b32 m0, s26
	s_nop 0
	global_load_lds_dwordx4 v[218:219], off
	v_lshl_add_u64 v[218:219], s[24:25], 0, v[138:139]
	s_add_i32 m0, s26, 0x2000
	s_nop 0
	global_load_lds_dwordx4 v[218:219], off
	s_waitcnt vmcnt(6)
	s_waitcnt lgkmcnt(0)
	s_barrier
	v_mfma_f32_16x16x32_bf16 v[62:65], v[144:147], v[186:189], v[62:65]
	v_mfma_f32_16x16x32_bf16 v[58:61], v[160:163], v[186:189], v[58:61]
	v_mfma_f32_16x16x32_bf16 v[46:49], v[144:147], v[194:197], v[46:49]
	v_mfma_f32_16x16x32_bf16 v[42:45], v[160:163], v[194:197], v[42:45]
	v_mfma_f32_16x16x32_bf16 v[30:33], v[144:147], v[202:205], v[30:33]
	v_mfma_f32_16x16x32_bf16 v[26:29], v[160:163], v[202:205], v[26:29]
	v_mfma_f32_16x16x32_bf16 v[14:17], v[144:147], v[210:213], v[14:17]
	v_mfma_f32_16x16x32_bf16 v[10:13], v[160:163], v[210:213], v[10:13]
	v_mfma_f32_16x16x32_bf16 v[62:65], v[156:159], v[190:193], v[62:65]
	v_mfma_f32_16x16x32_bf16 v[58:61], v[166:169], v[190:193], v[58:61]
	v_mfma_f32_16x16x32_bf16 v[46:49], v[156:159], v[198:201], v[46:49]
	v_mfma_f32_16x16x32_bf16 v[42:45], v[166:169], v[198:201], v[42:45]
	v_mfma_f32_16x16x32_bf16 v[30:33], v[156:159], v[206:209], v[30:33]
	v_mfma_f32_16x16x32_bf16 v[26:29], v[166:169], v[206:209], v[26:29]
	v_mfma_f32_16x16x32_bf16 v[14:17], v[156:159], v[214:217], v[14:17]
	v_mfma_f32_16x16x32_bf16 v[10:13], v[166:169], v[214:217], v[10:13]
	v_mfma_f32_16x16x32_bf16 v[54:57], v[170:173], v[186:189], v[54:57]
	v_mfma_f32_16x16x32_bf16 v[50:53], v[178:181], v[186:189], v[50:53]
	v_mfma_f32_16x16x32_bf16 v[38:41], v[170:173], v[194:197], v[38:41]
	v_mfma_f32_16x16x32_bf16 v[34:37], v[178:181], v[194:197], v[34:37]
	v_mfma_f32_16x16x32_bf16 v[22:25], v[170:173], v[202:205], v[22:25]
	v_mfma_f32_16x16x32_bf16 v[18:21], v[178:181], v[202:205], v[18:21]
	v_mfma_f32_16x16x32_bf16 v[6:9], v[170:173], v[210:213], v[6:9]
	v_mfma_f32_16x16x32_bf16 v[2:5], v[178:181], v[210:213], v[2:5]
	v_mfma_f32_16x16x32_bf16 v[54:57], v[174:177], v[190:193], v[54:57]
	v_mfma_f32_16x16x32_bf16 v[50:53], v[182:185], v[190:193], v[50:53]
	v_mfma_f32_16x16x32_bf16 v[38:41], v[174:177], v[198:201], v[38:41]
	v_mfma_f32_16x16x32_bf16 v[34:37], v[182:185], v[198:201], v[34:37]
	v_mfma_f32_16x16x32_bf16 v[22:25], v[174:177], v[206:209], v[22:25]
	v_mfma_f32_16x16x32_bf16 v[18:21], v[182:185], v[206:209], v[18:21]
	v_mfma_f32_16x16x32_bf16 v[6:9], v[174:177], v[214:217], v[6:9]
	v_mfma_f32_16x16x32_bf16 v[2:5], v[182:185], v[214:217], v[2:5]
	s_barrier
	s_add_i32 s45, s45, 2
	s_add_u32 s22, s22, 0x100
	s_addc_u32 s23, s23, 0
	s_add_u32 s5, s5, 0x100
	s_addc_u32 s15, s15, 0
	s_cmp_gt_u32 s45, 29
	s_cbranch_scc0 .Lkback_704
	v_lshl_add_u64 v[244:245], v[222:223], 0, s[10:11]
	s_mov_b32 m0, s38
	s_nop 0
	global_load_lds_dwordx4 v[244:245], off
	v_lshl_add_u64 v[244:245], v[224:225], 0, s[10:11]
	s_mov_b32 m0, s39
	s_nop 0
	global_load_lds_dwordx4 v[244:245], off
	s_setprio 0
	s_and_b64 vcc, exec, s[12:13]
	s_cbranch_vccz .LBB0_707
	s_barrier

.LBB0_841:
	s_add_i32 s46, s45, -2
	s_add_u32 s4, s4, 0x60080
	s_addc_u32 s5, s5, 0
	s_add_u32 s47, s20, 0x100
	s_addc_u32 s48, s21, 0
	s_mov_b32 s20, 0
	s_and_b64 s[98:99], exec, s[10:11]
	s_cbranch_scc1 .Lsp_p5
	s_setprio 1
.Lsp_p5:
	s_branch .LBB0_842
.Lkback_842:
	v_lshl_add_u64 v[244:245], v[216:217], 0, s[8:9]
	s_mov_b32 m0, s34
	s_nop 0
	global_load_lds_dwordx4 v[244:245], off
	v_lshl_add_u64 v[244:245], v[218:219], 0, s[8:9]
	s_mov_b32 m0, s35
	s_nop 0
	global_load_lds_dwordx4 v[244:245], off
.LBB0_842:
	v_add_u32_e32 v158, s36, v152
	v_add_u32_e32 v162, s37, v152
	ds_read_b128 v[142:145], v158
	ds_read_b128 v[146:149], v158 offset:1024
	ds_read_b128 v[154:157], v158 offset:2048
	ds_read_b128 v[158:161], v158 offset:3072
	ds_read_b128 v[166:169], v162
	ds_read_b128 v[170:173], v162 offset:1024
	ds_read_b128 v[174:177], v162 offset:2048
	ds_read_b128 v[178:181], v162 offset:3072
	s_add_i32 s49, s20, 2
	s_add_u32 s21, s4, 0xfffa0080
	s_addc_u32 s22, s5, -1
	s_cmp_eq_u32 s46, s20
	s_cselect_b32 s20, s16, s47
	s_cselect_b32 s23, s15, s22
	s_cselect_b32 s22, s14, s21
	s_cselect_b32 s21, s17, s48
	v_lshl_add_u64 v[162:163], s[4:5], 0, v[138:139]
	s_add_i32 m0, s26, 0xc000
	ds_read_b128 v[182:185], v153
	ds_read_b128 v[186:189], v153 offset:1024
	ds_read_b128 v[190:193], v153 offset:2048
	ds_read_b128 v[194:197], v153 offset:3072
	ds_read_b128 v[198:201], v153 offset:4096
	ds_read_b128 v[202:205], v153 offset:5120
	ds_read_b128 v[206:209], v153 offset:6144
	ds_read_b128 v[210:213], v153 offset:7168
	global_load_lds_dwordx4 v[162:163], off
	v_lshl_add_u64 v[162:163], s[4:5], 0, v[140:141]
	s_add_i32 m0, s26, 0xe000
	s_nop 0
	global_load_lds_dwordx4 v[162:163], off
	s_waitcnt vmcnt(8)
	s_waitcnt lgkmcnt(0)
	s_barrier
	v_mfma_f32_16x16x32_bf16 v[126:129], v[142:145], v[182:185], v[126:129]
	v_mfma_f32_16x16x32_bf16 v[122:125], v[154:157], v[182:185], v[122:125]
	v_mfma_f32_16x16x32_bf16 v[118:121], v[142:145], v[190:193], v[118:121]
	v_mfma_f32_16x16x32_bf16 v[114:117], v[154:157], v[190:193], v[114:117]
	v_mfma_f32_16x16x32_bf16 v[110:113], v[142:145], v[198:201], v[110:113]
	v_mfma_f32_16x16x32_bf16 v[106:109], v[154:157], v[198:201], v[106:109]
	v_mfma_f32_16x16x32_bf16 v[102:105], v[142:145], v[206:209], v[102:105]
	v_mfma_f32_16x16x32_bf16 v[98:101], v[154:157], v[206:209], v[98:101]
	v_mfma_f32_16x16x32_bf16 v[126:129], v[146:149], v[186:189], v[126:129]
	v_mfma_f32_16x16x32_bf16 v[122:125], v[158:161], v[186:189], v[122:125]
	v_mfma_f32_16x16x32_bf16 v[118:121], v[146:149], v[194:197], v[118:121]
	v_mfma_f32_16x16x32_bf16 v[114:117], v[158:161], v[194:197], v[114:117]
	v_mfma_f32_16x16x32_bf16 v[110:113], v[146:149], v[202:205], v[110:113]
	v_mfma_f32_16x16x32_bf16 v[106:109], v[158:161], v[202:205], v[106:109]
	v_mfma_f32_16x16x32_bf16 v[102:105], v[146:149], v[210:213], v[102:105]
	v_mfma_f32_16x16x32_bf16 v[98:101], v[158:161], v[210:213], v[98:101]
	v_mfma_f32_16x16x32_bf16 v[94:97], v[166:169], v[182:185], v[94:97]
	v_mfma_f32_16x16x32_bf16 v[90:93], v[174:177], v[182:185], v[90:93]
	v_mfma_f32_16x16x32_bf16 v[86:89], v[166:169], v[190:193], v[86:89]
	v_mfma_f32_16x16x32_bf16 v[82:85], v[174:177], v[190:193], v[82:85]
	v_mfma_f32_16x16x32_bf16 v[78:81], v[166:169], v[198:201], v[78:81]
	v_mfma_f32_16x16x32_bf16 v[74:77], v[174:177], v[198:201], v[74:77]
	v_mfma_f32_16x16x32_bf16 v[70:73], v[166:169], v[206:209], v[70:73]
	v_mfma_f32_16x16x32_bf16 v[66:69], v[174:177], v[206:209], v[66:69]
	v_mfma_f32_16x16x32_bf16 v[94:97], v[170:173], v[186:189], v[94:97]
	v_mfma_f32_16x16x32_bf16 v[90:93], v[178:181], v[186:189], v[90:93]
	v_mfma_f32_16x16x32_bf16 v[86:89], v[170:173], v[194:197], v[86:89]
	v_mfma_f32_16x16x32_bf16 v[82:85], v[178:181], v[194:197], v[82:85]
	v_mfma_f32_16x16x32_bf16 v[78:81], v[170:173], v[202:205], v[78:81]
	v_mfma_f32_16x16x32_bf16 v[74:77], v[178:181], v[202:205], v[74:77]
	v_mfma_f32_16x16x32_bf16 v[70:73], v[170:173], v[210:213], v[70:73]
	v_mfma_f32_16x16x32_bf16 v[66:69], v[178:181], v[210:213], v[66:69]
	s_barrier
	s_add_i32 s50, s36, s25
	v_lshl_add_u64 v[162:163], s[20:21], 0, v[132:133]
	s_mov_b32 m0, s50
	ds_read_b128 v[182:185], v153 offset:16384
	ds_read_b128 v[186:189], v153 offset:17408
	ds_read_b128 v[190:193], v153 offset:18432
	ds_read_b128 v[194:197], v153 offset:19456
	ds_read_b128 v[198:201], v153 offset:20480
	ds_read_b128 v[202:205], v153 offset:21504
	ds_read_b128 v[206:209], v153 offset:22528
	ds_read_b128 v[210:213], v153 offset:23552
	global_load_lds_dwordx4 v[162:163], off
	s_add_i32 m0, s50, 0x2000
	s_add_u32 s50, s20, 0x60000
	v_lshl_add_u64 v[214:215], s[20:21], 0, v[136:137]
	s_addc_u32 s51, s21, 0
	s_add_i32 s52, s37, s25
	global_load_lds_dwordx4 v[214:215], off
	v_lshl_add_u64 v[216:217], s[50:51], 0, v[132:133]
	s_mov_b32 m0, s52
	v_lshl_add_u64 v[218:219], s[22:23], 0, v[134:135]
	global_load_lds_dwordx4 v[216:217], off
	v_lshl_add_u64 v[216:217], s[50:51], 0, v[136:137]
	s_add_i32 m0, s52, 0x2000
	s_nop 0
	global_load_lds_dwordx4 v[216:217], off
	v_lshl_add_u64 v[216:217], s[22:23], 0, v[130:131]
	s_waitcnt vmcnt(6)
	s_waitcnt lgkmcnt(0)
	s_barrier
	v_mfma_f32_16x16x32_bf16 v[62:65], v[142:145], v[182:185], v[62:65]
	v_mfma_f32_16x16x32_bf16 v[58:61], v[154:157], v[182:185], v[58:61]
	v_mfma_f32_16x16x32_bf16 v[54:57], v[142:145], v[190:193], v[54:57]
	v_mfma_f32_16x16x32_bf16 v[50:53], v[154:157], v[190:193], v[50:53]
	v_mfma_f32_16x16x32_bf16 v[46:49], v[142:145], v[198:201], v[46:49]
	v_mfma_f32_16x16x32_bf16 v[42:45], v[154:157], v[198:201], v[42:45]
	v_mfma_f32_16x16x32_bf16 v[38:41], v[142:145], v[206:209], v[38:41]
	v_mfma_f32_16x16x32_bf16 v[34:37], v[154:157], v[206:209], v[34:37]
	v_mfma_f32_16x16x32_bf16 v[62:65], v[146:149], v[186:189], v[62:65]
	v_mfma_f32_16x16x32_bf16 v[58:61], v[158:161], v[186:189], v[58:61]
	v_mfma_f32_16x16x32_bf16 v[54:57], v[146:149], v[194:197], v[54:57]
	v_mfma_f32_16x16x32_bf16 v[50:53], v[158:161], v[194:197], v[50:53]
	v_mfma_f32_16x16x32_bf16 v[46:49], v[146:149], v[202:205], v[46:49]
	v_mfma_f32_16x16x32_bf16 v[42:45], v[158:161], v[202:205], v[42:45]
	v_mfma_f32_16x16x32_bf16 v[38:41], v[146:149], v[210:213], v[38:41]
	v_mfma_f32_16x16x32_bf16 v[34:37], v[158:161], v[210:213], v[34:37]
	v_mfma_f32_16x16x32_bf16 v[30:33], v[166:169], v[182:185], v[30:33]
	v_mfma_f32_16x16x32_bf16 v[26:29], v[174:177], v[182:185], v[26:29]
	v_mfma_f32_16x16x32_bf16 v[22:25], v[166:169], v[190:193], v[22:25]
	v_mfma_f32_16x16x32_bf16 v[18:21], v[174:177], v[190:193], v[18:21]
	v_mfma_f32_16x16x32_bf16 v[14:17], v[166:169], v[198:201], v[14:17]
	v_mfma_f32_16x16x32_bf16 v[10:13], v[174:177], v[198:201], v[10:13]
	v_mfma_f32_16x16x32_bf16 v[6:9], v[166:169], v[206:209], v[6:9]
	v_mfma_f32_16x16x32_bf16 v[2:5], v[174:177], v[206:209], v[2:5]
	v_mfma_f32_16x16x32_bf16 v[30:33], v[170:173], v[186:189], v[30:33]
	v_mfma_f32_16x16x32_bf16 v[26:29], v[178:181], v[186:189], v[26:29]
	v_mfma_f32_16x16x32_bf16 v[22:25], v[170:173], v[194:197], v[22:25]
	v_mfma_f32_16x16x32_bf16 v[18:21], v[178:181], v[194:197], v[18:21]
	v_mfma_f32_16x16x32_bf16 v[14:17], v[170:173], v[202:205], v[14:17]
	v_mfma_f32_16x16x32_bf16 v[10:13], v[178:181], v[202:205], v[10:13]
	v_mfma_f32_16x16x32_bf16 v[6:9], v[170:173], v[210:213], v[6:9]
	v_mfma_f32_16x16x32_bf16 v[2:5], v[178:181], v[210:213], v[2:5]
	s_barrier
	s_mov_b32 m0, s26
	s_nop 0
	global_load_lds_dwordx4 v[216:217], off
	s_mov_b32 m0, s27
	s_nop 0
	global_load_lds_dwordx4 v[218:219], off
	s_add_i32 s50, 0, 0x18000
	s_add_i32 s51, 0, 0x1c000
	v_add_u32_e32 v158, s50, v152
	v_add_u32_e32 v164, s51, v152
	ds_read_b128 v[142:145], v158
	ds_read_b128 v[146:149], v158 offset:1024
	ds_read_b128 v[154:157], v158 offset:2048
	ds_read_b128 v[158:161], v158 offset:3072
	ds_read_b128 v[166:169], v164
	ds_read_b128 v[170:173], v164 offset:1024
	ds_read_b128 v[174:177], v164 offset:2048
	ds_read_b128 v[178:181], v164 offset:3072
	s_add_u32 s22, s22, 0x60000
	s_addc_u32 s23, s23, 0
	s_mov_b32 m0, s28
	v_lshl_add_u64 v[220:221], s[22:23], 0, v[130:131]
	ds_read_b128 v[182:185], v153 offset:32768
	ds_read_b128 v[186:189], v153 offset:33792
	ds_read_b128 v[190:193], v153 offset:34816
	ds_read_b128 v[194:197], v153 offset:35840
	ds_read_b128 v[198:201], v153 offset:36864
	ds_read_b128 v[202:205], v153 offset:37888
	ds_read_b128 v[206:209], v153 offset:38912
	ds_read_b128 v[210:213], v153 offset:39936
	global_load_lds_dwordx4 v[220:221], off
	v_lshl_add_u64 v[220:221], s[22:23], 0, v[134:135]
	s_mov_b32 m0, s29
	s_nop 0
	global_load_lds_dwordx4 v[220:221], off
	s_waitcnt vmcnt(8)
	s_waitcnt lgkmcnt(0)
	s_barrier
	v_mfma_f32_16x16x32_bf16 v[126:129], v[142:145], v[182:185], v[126:129]
	v_mfma_f32_16x16x32_bf16 v[122:125], v[154:157], v[182:185], v[122:125]
	v_mfma_f32_16x16x32_bf16 v[118:121], v[142:145], v[190:193], v[118:121]
	v_mfma_f32_16x16x32_bf16 v[114:117], v[154:157], v[190:193], v[114:117]
	v_mfma_f32_16x16x32_bf16 v[110:113], v[142:145], v[198:201], v[110:113]
	v_mfma_f32_16x16x32_bf16 v[106:109], v[154:157], v[198:201], v[106:109]
	v_mfma_f32_16x16x32_bf16 v[102:105], v[142:145], v[206:209], v[102:105]
	v_mfma_f32_16x16x32_bf16 v[98:101], v[154:157], v[206:209], v[98:101]
	v_mfma_f32_16x16x32_bf16 v[126:129], v[146:149], v[186:189], v[126:129]
	v_mfma_f32_16x16x32_bf16 v[122:125], v[158:161], v[186:189], v[122:125]
	v_mfma_f32_16x16x32_bf16 v[118:121], v[146:149], v[194:197], v[118:121]
	v_mfma_f32_16x16x32_bf16 v[114:117], v[158:161], v[194:197], v[114:117]
	v_mfma_f32_16x16x32_bf16 v[110:113], v[146:149], v[202:205], v[110:113]
	v_mfma_f32_16x16x32_bf16 v[106:109], v[158:161], v[202:205], v[106:109]
	v_mfma_f32_16x16x32_bf16 v[102:105], v[146:149], v[210:213], v[102:105]
	v_mfma_f32_16x16x32_bf16 v[98:101], v[158:161], v[210:213], v[98:101]
	v_mfma_f32_16x16x32_bf16 v[94:97], v[166:169], v[182:185], v[94:97]
	v_mfma_f32_16x16x32_bf16 v[90:93], v[174:177], v[182:185], v[90:93]
	v_mfma_f32_16x16x32_bf16 v[86:89], v[166:169], v[190:193], v[86:89]
	v_mfma_f32_16x16x32_bf16 v[82:85], v[174:177], v[190:193], v[82:85]
	v_mfma_f32_16x16x32_bf16 v[78:81], v[166:169], v[198:201], v[78:81]
	v_mfma_f32_16x16x32_bf16 v[74:77], v[174:177], v[198:201], v[74:77]
	v_mfma_f32_16x16x32_bf16 v[70:73], v[166:169], v[206:209], v[70:73]
	v_mfma_f32_16x16x32_bf16 v[66:69], v[174:177], v[206:209], v[66:69]
	v_mfma_f32_16x16x32_bf16 v[94:97], v[170:173], v[186:189], v[94:97]
	v_mfma_f32_16x16x32_bf16 v[90:93], v[178:181], v[186:189], v[90:93]
	v_mfma_f32_16x16x32_bf16 v[86:89], v[170:173], v[194:197], v[86:89]
	v_mfma_f32_16x16x32_bf16 v[82:85], v[178:181], v[194:197], v[82:85]
	v_mfma_f32_16x16x32_bf16 v[78:81], v[170:173], v[202:205], v[78:81]
	v_mfma_f32_16x16x32_bf16 v[74:77], v[178:181], v[202:205], v[74:77]
	v_mfma_f32_16x16x32_bf16 v[70:73], v[170:173], v[210:213], v[70:73]
	v_mfma_f32_16x16x32_bf16 v[66:69], v[178:181], v[210:213], v[66:69]
	s_barrier
	s_add_i32 s22, s50, s25
	v_lshl_add_u64 v[162:163], v[162:163], 0, s[8:9]
	s_mov_b32 m0, s22
	ds_read_b128 v[182:185], v153 offset:49152
	ds_read_b128 v[186:189], v153 offset:50176
	ds_read_b128 v[190:193], v153 offset:51200
	ds_read_b128 v[194:197], v153 offset:52224
	ds_read_b128 v[198:201], v153 offset:53248
	ds_read_b128 v[202:205], v153 offset:54272
	ds_read_b128 v[206:209], v153 offset:55296
	ds_read_b128 v[210:213], v153 offset:56320
	global_load_lds_dwordx4 v[162:163], off
	s_add_i32 m0, s22, 0x2000
	s_add_u32 s20, s20, 0x60080
	v_lshl_add_u64 v[162:163], v[214:215], 0, s[8:9]
	s_addc_u32 s21, s21, 0
	s_add_i32 s22, s51, s25
	global_load_lds_dwordx4 v[162:163], off
	v_lshl_add_u64 v[162:163], s[20:21], 0, v[132:133]
	s_mov_b32 m0, s22
	s_nop 0
	global_load_lds_dwordx4 v[162:163], off
	v_lshl_add_u64 v[162:163], s[20:21], 0, v[136:137]
	s_add_i32 m0, s22, 0x2000
	s_nop 0
	global_load_lds_dwordx4 v[162:163], off
	s_waitcnt vmcnt(6)
	s_waitcnt lgkmcnt(0)
	s_barrier
	v_mfma_f32_16x16x32_bf16 v[62:65], v[142:145], v[182:185], v[62:65]
	v_mfma_f32_16x16x32_bf16 v[58:61], v[154:157], v[182:185], v[58:61]
	v_mfma_f32_16x16x32_bf16 v[54:57], v[142:145], v[190:193], v[54:57]
	v_mfma_f32_16x16x32_bf16 v[50:53], v[154:157], v[190:193], v[50:53]
	v_mfma_f32_16x16x32_bf16 v[46:49], v[142:145], v[198:201], v[46:49]
	v_mfma_f32_16x16x32_bf16 v[42:45], v[154:157], v[198:201], v[42:45]
	v_mfma_f32_16x16x32_bf16 v[38:41], v[142:145], v[206:209], v[38:41]
	v_mfma_f32_16x16x32_bf16 v[34:37], v[154:157], v[206:209], v[34:37]
	v_mfma_f32_16x16x32_bf16 v[62:65], v[146:149], v[186:189], v[62:65]
	v_mfma_f32_16x16x32_bf16 v[58:61], v[158:161], v[186:189], v[58:61]
	v_mfma_f32_16x16x32_bf16 v[54:57], v[146:149], v[194:197], v[54:57]
	v_mfma_f32_16x16x32_bf16 v[50:53], v[158:161], v[194:197], v[50:53]
	v_mfma_f32_16x16x32_bf16 v[46:49], v[146:149], v[202:205], v[46:49]
	v_mfma_f32_16x16x32_bf16 v[42:45], v[158:161], v[202:205], v[42:45]
	v_mfma_f32_16x16x32_bf16 v[38:41], v[146:149], v[210:213], v[38:41]
	v_mfma_f32_16x16x32_bf16 v[34:37], v[158:161], v[210:213], v[34:37]
	v_mfma_f32_16x16x32_bf16 v[30:33], v[166:169], v[182:185], v[30:33]
	v_mfma_f32_16x16x32_bf16 v[26:29], v[174:177], v[182:185], v[26:29]
	v_mfma_f32_16x16x32_bf16 v[22:25], v[166:169], v[190:193], v[22:25]
	v_mfma_f32_16x16x32_bf16 v[18:21], v[174:177], v[190:193], v[18:21]
	v_mfma_f32_16x16x32_bf16 v[14:17], v[166:169], v[198:201], v[14:17]
	v_mfma_f32_16x16x32_bf16 v[10:13], v[174:177], v[198:201], v[10:13]
	v_mfma_f32_16x16x32_bf16 v[6:9], v[166:169], v[206:209], v[6:9]
	v_mfma_f32_16x16x32_bf16 v[2:5], v[174:177], v[206:209], v[2:5]
	v_mfma_f32_16x16x32_bf16 v[30:33], v[170:173], v[186:189], v[30:33]
	v_mfma_f32_16x16x32_bf16 v[26:29], v[178:181], v[186:189], v[26:29]
	v_mfma_f32_16x16x32_bf16 v[22:25], v[170:173], v[194:197], v[22:25]
	v_mfma_f32_16x16x32_bf16 v[18:21], v[178:181], v[194:197], v[18:21]
	v_mfma_f32_16x16x32_bf16 v[14:17], v[170:173], v[202:205], v[14:17]
	v_mfma_f32_16x16x32_bf16 v[10:13], v[178:181], v[202:205], v[10:13]
	v_mfma_f32_16x16x32_bf16 v[6:9], v[170:173], v[210:213], v[6:9]
	v_mfma_f32_16x16x32_bf16 v[2:5], v[178:181], v[210:213], v[2:5]
	s_barrier
	s_add_u32 s4, s4, 0x100
	s_addc_u32 s5, s5, 0
	s_add_u32 s47, s47, 0x100
	s_addc_u32 s48, s48, 0
	s_cmp_ge_i32 s49, s45
	s_mov_b32 s20, s49
	s_cbranch_scc0 .Lkback_842
	v_lshl_add_u64 v[244:245], v[216:217], 0, s[8:9]
	s_mov_b32 m0, s34
	s_nop 0
	global_load_lds_dwordx4 v[244:245], off
	v_lshl_add_u64 v[244:245], v[218:219], 0, s[8:9]
	s_mov_b32 m0, s35
	s_nop 0
	global_load_lds_dwordx4 v[244:245], off
	s_setprio 0
	s_and_b64 vcc, exec, s[10:11]
	s_cbranch_vccz .LBB0_845
	s_barrier

.LBB0_1018:
	s_and_b64 s[30:31], s[22:23], exec
	s_cselect_b32 s1, s19, s27
	s_cselect_b32 s15, s18, s26
	s_cselect_b32 s17, s21, s29
	s_cselect_b32 s46, s20, s28
	s_add_u32 s26, s26, 0x80080
	s_addc_u32 s27, s27, 0
	s_add_u32 s47, s28, 0x100
	v_mov_b32_e32 v2, 0
	s_addc_u32 s48, s29, 0
	s_mov_b32 s49, -2
	s_waitcnt lgkmcnt(0)
	v_mov_b32_e32 v3, v2
	v_mov_b32_e32 v4, v2
	v_mov_b32_e32 v5, v2
	v_mov_b32_e32 v6, v2
	v_mov_b32_e32 v7, v2
	v_mov_b32_e32 v8, v2
	v_mov_b32_e32 v9, v2
	v_mov_b32_e32 v18, v2
	v_mov_b32_e32 v19, v2
	v_mov_b32_e32 v20, v2
	v_mov_b32_e32 v21, v2
	v_mov_b32_e32 v22, v2
	v_mov_b32_e32 v23, v2
	v_mov_b32_e32 v24, v2
	v_mov_b32_e32 v25, v2
	v_mov_b32_e32 v34, v2
	v_mov_b32_e32 v35, v2
	v_mov_b32_e32 v36, v2
	v_mov_b32_e32 v37, v2
	v_mov_b32_e32 v38, v2
	v_mov_b32_e32 v39, v2
	v_mov_b32_e32 v40, v2
	v_mov_b32_e32 v41, v2
	v_mov_b32_e32 v50, v2
	v_mov_b32_e32 v51, v2
	v_mov_b32_e32 v52, v2
	v_mov_b32_e32 v53, v2
	v_mov_b32_e32 v54, v2
	v_mov_b32_e32 v55, v2
	v_mov_b32_e32 v56, v2
	v_mov_b32_e32 v57, v2
	v_mov_b32_e32 v10, v2
	v_mov_b32_e32 v11, v2
	v_mov_b32_e32 v12, v2
	v_mov_b32_e32 v13, v2
	v_mov_b32_e32 v14, v2
	v_mov_b32_e32 v15, v2
	v_mov_b32_e32 v16, v2
	v_mov_b32_e32 v17, v2
	v_mov_b32_e32 v26, v2
	v_mov_b32_e32 v27, v2
	v_mov_b32_e32 v28, v2
	v_mov_b32_e32 v29, v2
	v_mov_b32_e32 v30, v2
	v_mov_b32_e32 v31, v2
	v_mov_b32_e32 v32, v2
	v_mov_b32_e32 v33, v2
	v_mov_b32_e32 v42, v2
	v_mov_b32_e32 v43, v2
	v_mov_b32_e32 v44, v2
	v_mov_b32_e32 v45, v2
	v_mov_b32_e32 v46, v2
	v_mov_b32_e32 v47, v2
	v_mov_b32_e32 v48, v2
	v_mov_b32_e32 v49, v2
	v_mov_b32_e32 v58, v2
	v_mov_b32_e32 v59, v2
	v_mov_b32_e32 v60, v2
	v_mov_b32_e32 v61, v2
	v_mov_b32_e32 v62, v2
	v_mov_b32_e32 v63, v2
	v_mov_b32_e32 v64, v2
	v_mov_b32_e32 v65, v2
	v_mov_b32_e32 v66, v2
	v_mov_b32_e32 v67, v2
	v_mov_b32_e32 v68, v2
	v_mov_b32_e32 v69, v2
	v_mov_b32_e32 v70, v2
	v_mov_b32_e32 v71, v2
	v_mov_b32_e32 v72, v2
	v_mov_b32_e32 v73, v2
	v_mov_b32_e32 v82, v2
	v_mov_b32_e32 v83, v2
	v_mov_b32_e32 v84, v2
	v_mov_b32_e32 v85, v2
	v_mov_b32_e32 v86, v2
	v_mov_b32_e32 v87, v2
	v_mov_b32_e32 v88, v2
	v_mov_b32_e32 v89, v2
	v_mov_b32_e32 v98, v2
	v_mov_b32_e32 v99, v2
	v_mov_b32_e32 v100, v2
	v_mov_b32_e32 v101, v2
	v_mov_b32_e32 v102, v2
	v_mov_b32_e32 v103, v2
	v_mov_b32_e32 v104, v2
	v_mov_b32_e32 v105, v2
	v_mov_b32_e32 v114, v2
	v_mov_b32_e32 v115, v2
	v_mov_b32_e32 v116, v2
	v_mov_b32_e32 v117, v2
	v_mov_b32_e32 v118, v2
	v_mov_b32_e32 v119, v2
	v_mov_b32_e32 v120, v2
	v_mov_b32_e32 v121, v2
	v_mov_b32_e32 v74, v2
	v_mov_b32_e32 v75, v2
	v_mov_b32_e32 v76, v2
	v_mov_b32_e32 v77, v2
	v_mov_b32_e32 v78, v2
	v_mov_b32_e32 v79, v2
	v_mov_b32_e32 v80, v2
	v_mov_b32_e32 v81, v2
	v_mov_b32_e32 v90, v2
	v_mov_b32_e32 v91, v2
	v_mov_b32_e32 v92, v2
	v_mov_b32_e32 v93, v2
	v_mov_b32_e32 v94, v2
	v_mov_b32_e32 v95, v2
	v_mov_b32_e32 v96, v2
	v_mov_b32_e32 v97, v2
	v_mov_b32_e32 v106, v2
	v_mov_b32_e32 v107, v2
	v_mov_b32_e32 v108, v2
	v_mov_b32_e32 v109, v2
	v_mov_b32_e32 v110, v2
	v_mov_b32_e32 v111, v2
	v_mov_b32_e32 v112, v2
	v_mov_b32_e32 v113, v2
	v_mov_b32_e32 v122, v2
	v_mov_b32_e32 v123, v2
	v_mov_b32_e32 v124, v2
	v_mov_b32_e32 v125, v2
	v_mov_b32_e32 v126, v2
	v_mov_b32_e32 v127, v2
	v_mov_b32_e32 v128, v2
	v_mov_b32_e32 v129, v2
	s_and_b64 s[98:99], exec, s[10:11]
	s_cbranch_scc1 .Lsp_p6
	s_setprio 1
.Lsp_p6:
	s_branch .LBB0_1019
.Lkback_1019:
	v_lshl_add_u64 v[244:245], v[220:221], 0, s[8:9]
	s_mov_b32 m0, s41
	s_nop 0
	global_load_lds_dwordx4 v[244:245], off
	v_lshl_add_u64 v[244:245], v[222:223], 0, s[8:9]
	s_mov_b32 m0, s42
	s_nop 0
	global_load_lds_dwordx4 v[244:245], off
.LBB0_1019:
	ds_read_b128 v[142:145], v149
	ds_read_b128 v[154:157], v149 offset:1024
	ds_read_b128 v[158:161], v149 offset:2048
	ds_read_b128 v[166:169], v149 offset:3072
	ds_read_b128 v[170:173], v150
	ds_read_b128 v[174:177], v150 offset:1024
	ds_read_b128 v[178:181], v150 offset:2048
	ds_read_b128 v[182:185], v150 offset:3072
	s_add_u32 s28, s26, 0xfff80080
	s_addc_u32 s29, s27, -1
	s_cmp_eq_u32 s49, 28
	s_cselect_b32 s31, s1, s29
	s_cselect_b32 s30, s15, s28
	s_cselect_b32 s29, s17, s48
	s_cselect_b32 s28, s46, s47
	v_lshl_add_u64 v[162:163], s[26:27], 0, v[138:139]
	s_add_i32 m0, s34, 0xc000
	ds_read_b128 v[186:189], v151
	ds_read_b128 v[190:193], v151 offset:1024
	ds_read_b128 v[194:197], v151 offset:2048
	ds_read_b128 v[198:201], v151 offset:3072
	ds_read_b128 v[202:205], v151 offset:4096
	ds_read_b128 v[206:209], v151 offset:5120
	ds_read_b128 v[210:213], v151 offset:6144
	ds_read_b128 v[214:217], v151 offset:7168
	global_load_lds_dwordx4 v[162:163], off
	v_lshl_add_u64 v[162:163], s[26:27], 0, v[140:141]
	s_add_i32 m0, s34, 0xe000
	s_nop 0
	global_load_lds_dwordx4 v[162:163], off
	s_waitcnt vmcnt(8)
	s_waitcnt lgkmcnt(0)
	s_barrier
	v_mfma_f32_16x16x32_bf16 v[126:129], v[142:145], v[186:189], v[126:129]
	v_mfma_f32_16x16x32_bf16 v[122:125], v[158:161], v[186:189], v[122:125]
	v_mfma_f32_16x16x32_bf16 v[110:113], v[142:145], v[194:197], v[110:113]
	v_mfma_f32_16x16x32_bf16 v[106:109], v[158:161], v[194:197], v[106:109]
	v_mfma_f32_16x16x32_bf16 v[94:97], v[142:145], v[202:205], v[94:97]
	v_mfma_f32_16x16x32_bf16 v[90:93], v[158:161], v[202:205], v[90:93]
	v_mfma_f32_16x16x32_bf16 v[78:81], v[142:145], v[210:213], v[78:81]
	v_mfma_f32_16x16x32_bf16 v[74:77], v[158:161], v[210:213], v[74:77]
	v_mfma_f32_16x16x32_bf16 v[126:129], v[154:157], v[190:193], v[126:129]
	v_mfma_f32_16x16x32_bf16 v[122:125], v[166:169], v[190:193], v[122:125]
	v_mfma_f32_16x16x32_bf16 v[110:113], v[154:157], v[198:201], v[110:113]
	v_mfma_f32_16x16x32_bf16 v[106:109], v[166:169], v[198:201], v[106:109]
	v_mfma_f32_16x16x32_bf16 v[94:97], v[154:157], v[206:209], v[94:97]
	v_mfma_f32_16x16x32_bf16 v[90:93], v[166:169], v[206:209], v[90:93]
	v_mfma_f32_16x16x32_bf16 v[78:81], v[154:157], v[214:217], v[78:81]
	v_mfma_f32_16x16x32_bf16 v[74:77], v[166:169], v[214:217], v[74:77]
	v_mfma_f32_16x16x32_bf16 v[118:121], v[170:173], v[186:189], v[118:121]
	v_mfma_f32_16x16x32_bf16 v[114:117], v[178:181], v[186:189], v[114:117]
	v_mfma_f32_16x16x32_bf16 v[102:105], v[170:173], v[194:197], v[102:105]
	v_mfma_f32_16x16x32_bf16 v[98:101], v[178:181], v[194:197], v[98:101]
	v_mfma_f32_16x16x32_bf16 v[86:89], v[170:173], v[202:205], v[86:89]
	v_mfma_f32_16x16x32_bf16 v[82:85], v[178:181], v[202:205], v[82:85]
	v_mfma_f32_16x16x32_bf16 v[70:73], v[170:173], v[210:213], v[70:73]
	v_mfma_f32_16x16x32_bf16 v[66:69], v[178:181], v[210:213], v[66:69]
	v_mfma_f32_16x16x32_bf16 v[118:121], v[174:177], v[190:193], v[118:121]
	v_mfma_f32_16x16x32_bf16 v[114:117], v[182:185], v[190:193], v[114:117]
	v_mfma_f32_16x16x32_bf16 v[102:105], v[174:177], v[198:201], v[102:105]
	v_mfma_f32_16x16x32_bf16 v[98:101], v[182:185], v[198:201], v[98:101]
	v_mfma_f32_16x16x32_bf16 v[86:89], v[174:177], v[206:209], v[86:89]
	v_mfma_f32_16x16x32_bf16 v[82:85], v[182:185], v[206:209], v[82:85]
	v_mfma_f32_16x16x32_bf16 v[70:73], v[174:177], v[214:217], v[70:73]
	v_mfma_f32_16x16x32_bf16 v[66:69], v[182:185], v[214:217], v[66:69]
	s_barrier
	s_add_i32 s50, s44, s25
	v_lshl_add_u64 v[162:163], s[28:29], 0, v[132:133]
	s_mov_b32 m0, s50
	ds_read_b128 v[186:189], v151 offset:16384
	ds_read_b128 v[190:193], v151 offset:17408
	ds_read_b128 v[194:197], v151 offset:18432
	ds_read_b128 v[198:201], v151 offset:19456
	ds_read_b128 v[202:205], v151 offset:20480
	ds_read_b128 v[206:209], v151 offset:21504
	ds_read_b128 v[210:213], v151 offset:22528
	ds_read_b128 v[214:217], v151 offset:23552
	global_load_lds_dwordx4 v[162:163], off
	s_add_i32 m0, s50, 0x2000
	s_add_u32 s50, s28, 0x80000
	v_lshl_add_u64 v[218:219], s[28:29], 0, v[136:137]
	s_addc_u32 s51, s29, 0
	s_add_i32 s52, s45, s25
	global_load_lds_dwordx4 v[218:219], off
	v_lshl_add_u64 v[220:221], s[50:51], 0, v[132:133]
	s_mov_b32 m0, s52
	v_lshl_add_u64 v[222:223], s[30:31], 0, v[134:135]
	global_load_lds_dwordx4 v[220:221], off
	v_lshl_add_u64 v[220:221], s[50:51], 0, v[136:137]
	s_add_i32 m0, s52, 0x2000
	s_nop 0
	global_load_lds_dwordx4 v[220:221], off
	v_lshl_add_u64 v[220:221], s[30:31], 0, v[130:131]
	s_waitcnt vmcnt(6)
	s_waitcnt lgkmcnt(0)
	s_barrier
	v_mfma_f32_16x16x32_bf16 v[62:65], v[142:145], v[186:189], v[62:65]
	v_mfma_f32_16x16x32_bf16 v[58:61], v[158:161], v[186:189], v[58:61]
	v_mfma_f32_16x16x32_bf16 v[46:49], v[142:145], v[194:197], v[46:49]
	v_mfma_f32_16x16x32_bf16 v[42:45], v[158:161], v[194:197], v[42:45]
	v_mfma_f32_16x16x32_bf16 v[30:33], v[142:145], v[202:205], v[30:33]
	v_mfma_f32_16x16x32_bf16 v[26:29], v[158:161], v[202:205], v[26:29]
	v_mfma_f32_16x16x32_bf16 v[14:17], v[142:145], v[210:213], v[14:17]
	v_mfma_f32_16x16x32_bf16 v[10:13], v[158:161], v[210:213], v[10:13]
	v_mfma_f32_16x16x32_bf16 v[62:65], v[154:157], v[190:193], v[62:65]
	v_mfma_f32_16x16x32_bf16 v[58:61], v[166:169], v[190:193], v[58:61]
	v_mfma_f32_16x16x32_bf16 v[46:49], v[154:157], v[198:201], v[46:49]
	v_mfma_f32_16x16x32_bf16 v[42:45], v[166:169], v[198:201], v[42:45]
	v_mfma_f32_16x16x32_bf16 v[30:33], v[154:157], v[206:209], v[30:33]
	v_mfma_f32_16x16x32_bf16 v[26:29], v[166:169], v[206:209], v[26:29]
	v_mfma_f32_16x16x32_bf16 v[14:17], v[154:157], v[214:217], v[14:17]
	v_mfma_f32_16x16x32_bf16 v[10:13], v[166:169], v[214:217], v[10:13]
	v_mfma_f32_16x16x32_bf16 v[54:57], v[170:173], v[186:189], v[54:57]
	v_mfma_f32_16x16x32_bf16 v[50:53], v[178:181], v[186:189], v[50:53]
	v_mfma_f32_16x16x32_bf16 v[38:41], v[170:173], v[194:197], v[38:41]
	v_mfma_f32_16x16x32_bf16 v[34:37], v[178:181], v[194:197], v[34:37]
	v_mfma_f32_16x16x32_bf16 v[22:25], v[170:173], v[202:205], v[22:25]
	v_mfma_f32_16x16x32_bf16 v[18:21], v[178:181], v[202:205], v[18:21]
	v_mfma_f32_16x16x32_bf16 v[6:9], v[170:173], v[210:213], v[6:9]
	v_mfma_f32_16x16x32_bf16 v[2:5], v[178:181], v[210:213], v[2:5]
	v_mfma_f32_16x16x32_bf16 v[54:57], v[174:177], v[190:193], v[54:57]
	v_mfma_f32_16x16x32_bf16 v[50:53], v[182:185], v[190:193], v[50:53]
	v_mfma_f32_16x16x32_bf16 v[38:41], v[174:177], v[198:201], v[38:41]
	v_mfma_f32_16x16x32_bf16 v[34:37], v[182:185], v[198:201], v[34:37]
	v_mfma_f32_16x16x32_bf16 v[22:25], v[174:177], v[206:209], v[22:25]
	v_mfma_f32_16x16x32_bf16 v[18:21], v[182:185], v[206:209], v[18:21]
	v_mfma_f32_16x16x32_bf16 v[6:9], v[174:177], v[214:217], v[6:9]
	v_mfma_f32_16x16x32_bf16 v[2:5], v[182:185], v[214:217], v[2:5]
	s_barrier
	s_mov_b32 m0, s34
	s_nop 0
	global_load_lds_dwordx4 v[220:221], off
	s_mov_b32 m0, s35
	s_nop 0
	global_load_lds_dwordx4 v[222:223], off
	s_add_i32 s50, 0, 0x18000
	v_add_u32_e32 v153, s50, v148
	s_add_i32 s51, 0, 0x1c000
	ds_read_b128 v[142:145], v153
	ds_read_b128 v[154:157], v153 offset:1024
	ds_read_b128 v[158:161], v153 offset:2048
	ds_read_b128 v[166:169], v153 offset:3072
	v_add_u32_e32 v153, s51, v148
	ds_read_b128 v[170:173], v153
	ds_read_b128 v[174:177], v153 offset:1024
	ds_read_b128 v[178:181], v153 offset:2048
	ds_read_b128 v[182:185], v153 offset:3072
	s_add_u32 s30, s30, 0x80000
	s_addc_u32 s31, s31, 0
	s_mov_b32 m0, s36
	v_lshl_add_u64 v[224:225], s[30:31], 0, v[130:131]
	ds_read_b128 v[186:189], v151 offset:32768
	ds_read_b128 v[190:193], v151 offset:33792
	ds_read_b128 v[194:197], v151 offset:34816
	ds_read_b128 v[198:201], v151 offset:35840
	ds_read_b128 v[202:205], v151 offset:36864
	ds_read_b128 v[206:209], v151 offset:37888
	ds_read_b128 v[210:213], v151 offset:38912
	ds_read_b128 v[214:217], v151 offset:39936
	global_load_lds_dwordx4 v[224:225], off
	v_lshl_add_u64 v[224:225], s[30:31], 0, v[134:135]
	s_mov_b32 m0, s37
	s_nop 0
	global_load_lds_dwordx4 v[224:225], off
	s_waitcnt vmcnt(8)
	s_waitcnt lgkmcnt(0)
	s_barrier
	v_mfma_f32_16x16x32_bf16 v[126:129], v[142:145], v[186:189], v[126:129]
	v_mfma_f32_16x16x32_bf16 v[122:125], v[158:161], v[186:189], v[122:125]
	v_mfma_f32_16x16x32_bf16 v[110:113], v[142:145], v[194:197], v[110:113]
	v_mfma_f32_16x16x32_bf16 v[106:109], v[158:161], v[194:197], v[106:109]
	v_mfma_f32_16x16x32_bf16 v[94:97], v[142:145], v[202:205], v[94:97]
	v_mfma_f32_16x16x32_bf16 v[90:93], v[158:161], v[202:205], v[90:93]
	v_mfma_f32_16x16x32_bf16 v[78:81], v[142:145], v[210:213], v[78:81]
	v_mfma_f32_16x16x32_bf16 v[74:77], v[158:161], v[210:213], v[74:77]
	v_mfma_f32_16x16x32_bf16 v[126:129], v[154:157], v[190:193], v[126:129]
	v_mfma_f32_16x16x32_bf16 v[122:125], v[166:169], v[190:193], v[122:125]
	v_mfma_f32_16x16x32_bf16 v[110:113], v[154:157], v[198:201], v[110:113]
	v_mfma_f32_16x16x32_bf16 v[106:109], v[166:169], v[198:201], v[106:109]
	v_mfma_f32_16x16x32_bf16 v[94:97], v[154:157], v[206:209], v[94:97]
	v_mfma_f32_16x16x32_bf16 v[90:93], v[166:169], v[206:209], v[90:93]
	v_mfma_f32_16x16x32_bf16 v[78:81], v[154:157], v[214:217], v[78:81]
	v_mfma_f32_16x16x32_bf16 v[74:77], v[166:169], v[214:217], v[74:77]
	v_mfma_f32_16x16x32_bf16 v[118:121], v[170:173], v[186:189], v[118:121]
	v_mfma_f32_16x16x32_bf16 v[114:117], v[178:181], v[186:189], v[114:117]
	v_mfma_f32_16x16x32_bf16 v[102:105], v[170:173], v[194:197], v[102:105]
	v_mfma_f32_16x16x32_bf16 v[98:101], v[178:181], v[194:197], v[98:101]
	v_mfma_f32_16x16x32_bf16 v[86:89], v[170:173], v[202:205], v[86:89]
	v_mfma_f32_16x16x32_bf16 v[82:85], v[178:181], v[202:205], v[82:85]
	v_mfma_f32_16x16x32_bf16 v[70:73], v[170:173], v[210:213], v[70:73]
	v_mfma_f32_16x16x32_bf16 v[66:69], v[178:181], v[210:213], v[66:69]
	v_mfma_f32_16x16x32_bf16 v[118:121], v[174:177], v[190:193], v[118:121]
	v_mfma_f32_16x16x32_bf16 v[114:117], v[182:185], v[190:193], v[114:117]
	v_mfma_f32_16x16x32_bf16 v[102:105], v[174:177], v[198:201], v[102:105]
	v_mfma_f32_16x16x32_bf16 v[98:101], v[182:185], v[198:201], v[98:101]
	v_mfma_f32_16x16x32_bf16 v[86:89], v[174:177], v[206:209], v[86:89]
	v_mfma_f32_16x16x32_bf16 v[82:85], v[182:185], v[206:209], v[82:85]
	v_mfma_f32_16x16x32_bf16 v[70:73], v[174:177], v[214:217], v[70:73]
	v_mfma_f32_16x16x32_bf16 v[66:69], v[182:185], v[214:217], v[66:69]
	s_barrier
	s_add_i32 s30, s50, s25
	v_lshl_add_u64 v[162:163], v[162:163], 0, s[8:9]
	s_mov_b32 m0, s30
	ds_read_b128 v[186:189], v151 offset:49152
	ds_read_b128 v[190:193], v151 offset:50176
	ds_read_b128 v[194:197], v151 offset:51200
	ds_read_b128 v[198:201], v151 offset:52224
	ds_read_b128 v[202:205], v151 offset:53248
	ds_read_b128 v[206:209], v151 offset:54272
	ds_read_b128 v[210:213], v151 offset:55296
	ds_read_b128 v[214:217], v151 offset:56320
	global_load_lds_dwordx4 v[162:163], off
	s_add_i32 m0, s30, 0x2000
	s_add_u32 s28, s28, 0x80080
	v_lshl_add_u64 v[162:163], v[218:219], 0, s[8:9]
	s_addc_u32 s29, s29, 0
	s_add_i32 s30, s51, s25
	global_load_lds_dwordx4 v[162:163], off
	v_lshl_add_u64 v[162:163], s[28:29], 0, v[132:133]
	s_mov_b32 m0, s30
	s_nop 0
	global_load_lds_dwordx4 v[162:163], off
	v_lshl_add_u64 v[162:163], s[28:29], 0, v[136:137]
	s_add_i32 m0, s30, 0x2000
	s_nop 0
	global_load_lds_dwordx4 v[162:163], off
	s_waitcnt vmcnt(6)
	s_waitcnt lgkmcnt(0)
	s_barrier
	v_mfma_f32_16x16x32_bf16 v[62:65], v[142:145], v[186:189], v[62:65]
	v_mfma_f32_16x16x32_bf16 v[58:61], v[158:161], v[186:189], v[58:61]
	v_mfma_f32_16x16x32_bf16 v[46:49], v[142:145], v[194:197], v[46:49]
	v_mfma_f32_16x16x32_bf16 v[42:45], v[158:161], v[194:197], v[42:45]
	v_mfma_f32_16x16x32_bf16 v[30:33], v[142:145], v[202:205], v[30:33]
	v_mfma_f32_16x16x32_bf16 v[26:29], v[158:161], v[202:205], v[26:29]
	v_mfma_f32_16x16x32_bf16 v[14:17], v[142:145], v[210:213], v[14:17]
	v_mfma_f32_16x16x32_bf16 v[10:13], v[158:161], v[210:213], v[10:13]
	v_mfma_f32_16x16x32_bf16 v[62:65], v[154:157], v[190:193], v[62:65]
	v_mfma_f32_16x16x32_bf16 v[58:61], v[166:169], v[190:193], v[58:61]
	v_mfma_f32_16x16x32_bf16 v[46:49], v[154:157], v[198:201], v[46:49]
	v_mfma_f32_16x16x32_bf16 v[42:45], v[166:169], v[198:201], v[42:45]
	v_mfma_f32_16x16x32_bf16 v[30:33], v[154:157], v[206:209], v[30:33]
	v_mfma_f32_16x16x32_bf16 v[26:29], v[166:169], v[206:209], v[26:29]
	v_mfma_f32_16x16x32_bf16 v[14:17], v[154:157], v[214:217], v[14:17]
	v_mfma_f32_16x16x32_bf16 v[10:13], v[166:169], v[214:217], v[10:13]
	v_mfma_f32_16x16x32_bf16 v[54:57], v[170:173], v[186:189], v[54:57]
	v_mfma_f32_16x16x32_bf16 v[50:53], v[178:181], v[186:189], v[50:53]
	v_mfma_f32_16x16x32_bf16 v[38:41], v[170:173], v[194:197], v[38:41]
	v_mfma_f32_16x16x32_bf16 v[34:37], v[178:181], v[194:197], v[34:37]
	v_mfma_f32_16x16x32_bf16 v[22:25], v[170:173], v[202:205], v[22:25]
	v_mfma_f32_16x16x32_bf16 v[18:21], v[178:181], v[202:205], v[18:21]
	v_mfma_f32_16x16x32_bf16 v[6:9], v[170:173], v[210:213], v[6:9]
	v_mfma_f32_16x16x32_bf16 v[2:5], v[178:181], v[210:213], v[2:5]
	v_mfma_f32_16x16x32_bf16 v[54:57], v[174:177], v[190:193], v[54:57]
	v_mfma_f32_16x16x32_bf16 v[50:53], v[182:185], v[190:193], v[50:53]
	v_mfma_f32_16x16x32_bf16 v[38:41], v[174:177], v[198:201], v[38:41]
	v_mfma_f32_16x16x32_bf16 v[34:37], v[182:185], v[198:201], v[34:37]
	v_mfma_f32_16x16x32_bf16 v[22:25], v[174:177], v[206:209], v[22:25]
	v_mfma_f32_16x16x32_bf16 v[18:21], v[182:185], v[206:209], v[18:21]
	v_mfma_f32_16x16x32_bf16 v[6:9], v[174:177], v[214:217], v[6:9]
	v_mfma_f32_16x16x32_bf16 v[2:5], v[182:185], v[214:217], v[2:5]
	s_barrier
	s_add_i32 s49, s49, 2
	s_add_u32 s26, s26, 0x100
	s_addc_u32 s27, s27, 0
	s_add_u32 s47, s47, 0x100
	s_addc_u32 s48, s48, 0
	s_cmp_gt_u32 s49, 29
	s_cbranch_scc0 .Lkback_1019
	v_lshl_add_u64 v[244:245], v[220:221], 0, s[8:9]
	s_mov_b32 m0, s41
	s_nop 0
	global_load_lds_dwordx4 v[244:245], off
	v_lshl_add_u64 v[244:245], v[222:223], 0, s[8:9]
	s_mov_b32 m0, s42
	s_nop 0
	global_load_lds_dwordx4 v[244:245], off
	s_setprio 0
	s_and_b64 vcc, exec, s[10:11]
	s_cbranch_vccz .LBB0_1022
	s_barrier

.LBB0_1219:
	s_and_b64 s[34:35], s[24:25], exec
	s_cselect_b32 s1, s21, s29
	s_cselect_b32 s17, s20, s28
	s_cselect_b32 s19, s23, s31
	s_cselect_b32 s48, s22, s30
	s_add_u32 s28, s28, 0x20080
	s_addc_u32 s29, s29, 0
	s_add_u32 s49, s30, 0x100
	v_mov_b32_e32 v2, 0
	s_addc_u32 s50, s31, 0
	s_mov_b32 s51, -2
	s_waitcnt lgkmcnt(0)
	v_mov_b32_e32 v3, v2
	v_mov_b32_e32 v4, v2
	v_mov_b32_e32 v5, v2
	v_mov_b32_e32 v6, v2
	v_mov_b32_e32 v7, v2
	v_mov_b32_e32 v8, v2
	v_mov_b32_e32 v9, v2
	v_mov_b32_e32 v18, v2
	v_mov_b32_e32 v19, v2
	v_mov_b32_e32 v20, v2
	v_mov_b32_e32 v21, v2
	v_mov_b32_e32 v22, v2
	v_mov_b32_e32 v23, v2
	v_mov_b32_e32 v24, v2
	v_mov_b32_e32 v25, v2
	v_mov_b32_e32 v34, v2
	v_mov_b32_e32 v35, v2
	v_mov_b32_e32 v36, v2
	v_mov_b32_e32 v37, v2
	v_mov_b32_e32 v38, v2
	v_mov_b32_e32 v39, v2
	v_mov_b32_e32 v40, v2
	v_mov_b32_e32 v41, v2
	v_mov_b32_e32 v50, v2
	v_mov_b32_e32 v51, v2
	v_mov_b32_e32 v52, v2
	v_mov_b32_e32 v53, v2
	v_mov_b32_e32 v54, v2
	v_mov_b32_e32 v55, v2
	v_mov_b32_e32 v56, v2
	v_mov_b32_e32 v57, v2
	v_mov_b32_e32 v10, v2
	v_mov_b32_e32 v11, v2
	v_mov_b32_e32 v12, v2
	v_mov_b32_e32 v13, v2
	v_mov_b32_e32 v14, v2
	v_mov_b32_e32 v15, v2
	v_mov_b32_e32 v16, v2
	v_mov_b32_e32 v17, v2
	v_mov_b32_e32 v26, v2
	v_mov_b32_e32 v27, v2
	v_mov_b32_e32 v28, v2
	v_mov_b32_e32 v29, v2
	v_mov_b32_e32 v30, v2
	v_mov_b32_e32 v31, v2
	v_mov_b32_e32 v32, v2
	v_mov_b32_e32 v33, v2
	v_mov_b32_e32 v42, v2
	v_mov_b32_e32 v43, v2
	v_mov_b32_e32 v44, v2
	v_mov_b32_e32 v45, v2
	v_mov_b32_e32 v46, v2
	v_mov_b32_e32 v47, v2
	v_mov_b32_e32 v48, v2
	v_mov_b32_e32 v49, v2
	v_mov_b32_e32 v58, v2
	v_mov_b32_e32 v59, v2
	v_mov_b32_e32 v60, v2
	v_mov_b32_e32 v61, v2
	v_mov_b32_e32 v62, v2
	v_mov_b32_e32 v63, v2
	v_mov_b32_e32 v64, v2
	v_mov_b32_e32 v65, v2
	v_mov_b32_e32 v66, v2
	v_mov_b32_e32 v67, v2
	v_mov_b32_e32 v68, v2
	v_mov_b32_e32 v69, v2
	v_mov_b32_e32 v70, v2
	v_mov_b32_e32 v71, v2
	v_mov_b32_e32 v72, v2
	v_mov_b32_e32 v73, v2
	v_mov_b32_e32 v82, v2
	v_mov_b32_e32 v83, v2
	v_mov_b32_e32 v84, v2
	v_mov_b32_e32 v85, v2
	v_mov_b32_e32 v86, v2
	v_mov_b32_e32 v87, v2
	v_mov_b32_e32 v88, v2
	v_mov_b32_e32 v89, v2
	v_mov_b32_e32 v98, v2
	v_mov_b32_e32 v99, v2
	v_mov_b32_e32 v100, v2
	v_mov_b32_e32 v101, v2
	v_mov_b32_e32 v102, v2
	v_mov_b32_e32 v103, v2
	v_mov_b32_e32 v104, v2
	v_mov_b32_e32 v105, v2
	v_mov_b32_e32 v114, v2
	v_mov_b32_e32 v115, v2
	v_mov_b32_e32 v116, v2
	v_mov_b32_e32 v117, v2
	v_mov_b32_e32 v118, v2
	v_mov_b32_e32 v119, v2
	v_mov_b32_e32 v120, v2
	v_mov_b32_e32 v121, v2
	v_mov_b32_e32 v74, v2
	v_mov_b32_e32 v75, v2
	v_mov_b32_e32 v76, v2
	v_mov_b32_e32 v77, v2
	v_mov_b32_e32 v78, v2
	v_mov_b32_e32 v79, v2
	v_mov_b32_e32 v80, v2
	v_mov_b32_e32 v81, v2
	v_mov_b32_e32 v90, v2
	v_mov_b32_e32 v91, v2
	v_mov_b32_e32 v92, v2
	v_mov_b32_e32 v93, v2
	v_mov_b32_e32 v94, v2
	v_mov_b32_e32 v95, v2
	v_mov_b32_e32 v96, v2
	v_mov_b32_e32 v97, v2
	v_mov_b32_e32 v106, v2
	v_mov_b32_e32 v107, v2
	v_mov_b32_e32 v108, v2
	v_mov_b32_e32 v109, v2
	v_mov_b32_e32 v110, v2
	v_mov_b32_e32 v111, v2
	v_mov_b32_e32 v112, v2
	v_mov_b32_e32 v113, v2
	v_mov_b32_e32 v122, v2
	v_mov_b32_e32 v123, v2
	v_mov_b32_e32 v124, v2
	v_mov_b32_e32 v125, v2
	v_mov_b32_e32 v126, v2
	v_mov_b32_e32 v127, v2
	v_mov_b32_e32 v128, v2
	v_mov_b32_e32 v129, v2
	s_and_b64 s[98:99], exec, s[12:13]
	s_cbranch_scc1 .Lsp_p9
	s_setprio 1
.Lsp_p9:
	s_branch .LBB0_1220
.Lkback_1220:
	v_lshl_add_u64 v[244:245], v[220:221], 0, s[10:11]
	s_mov_b32 m0, s43
	s_nop 0
	global_load_lds_dwordx4 v[244:245], off
	v_lshl_add_u64 v[244:245], v[222:223], 0, s[10:11]
	s_mov_b32 m0, s44
	s_nop 0
	global_load_lds_dwordx4 v[244:245], off
.LBB0_1220:
	ds_read_b128 v[142:145], v149
	ds_read_b128 v[154:157], v149 offset:1024
	ds_read_b128 v[158:161], v149 offset:2048
	ds_read_b128 v[166:169], v149 offset:3072
	ds_read_b128 v[170:173], v150
	ds_read_b128 v[174:177], v150 offset:1024
	ds_read_b128 v[178:181], v150 offset:2048
	ds_read_b128 v[182:185], v150 offset:3072
	s_add_u32 s30, s28, 0xfffe0080
	s_addc_u32 s31, s29, -1
	s_cmp_eq_u32 s51, 4
	s_cselect_b32 s35, s1, s31
	s_cselect_b32 s34, s17, s30
	s_cselect_b32 s31, s19, s50
	s_cselect_b32 s30, s48, s49
	v_lshl_add_u64 v[162:163], s[28:29], 0, v[138:139]
	s_add_i32 m0, s27, 0xc000
	ds_read_b128 v[186:189], v151
	ds_read_b128 v[190:193], v151 offset:1024
	ds_read_b128 v[194:197], v151 offset:2048
	ds_read_b128 v[198:201], v151 offset:3072
	ds_read_b128 v[202:205], v151 offset:4096
	ds_read_b128 v[206:209], v151 offset:5120
	ds_read_b128 v[210:213], v151 offset:6144
	ds_read_b128 v[214:217], v151 offset:7168
	global_load_lds_dwordx4 v[162:163], off
	v_lshl_add_u64 v[162:163], s[28:29], 0, v[140:141]
	s_add_i32 m0, s27, 0xe000
	s_nop 0
	global_load_lds_dwordx4 v[162:163], off
	s_waitcnt vmcnt(8)
	s_waitcnt lgkmcnt(0)
	s_barrier
	v_mfma_f32_16x16x32_bf16 v[126:129], v[142:145], v[186:189], v[126:129]
	v_mfma_f32_16x16x32_bf16 v[122:125], v[158:161], v[186:189], v[122:125]
	v_mfma_f32_16x16x32_bf16 v[110:113], v[142:145], v[194:197], v[110:113]
	v_mfma_f32_16x16x32_bf16 v[106:109], v[158:161], v[194:197], v[106:109]
	v_mfma_f32_16x16x32_bf16 v[94:97], v[142:145], v[202:205], v[94:97]
	v_mfma_f32_16x16x32_bf16 v[90:93], v[158:161], v[202:205], v[90:93]
	v_mfma_f32_16x16x32_bf16 v[78:81], v[142:145], v[210:213], v[78:81]
	v_mfma_f32_16x16x32_bf16 v[74:77], v[158:161], v[210:213], v[74:77]
	v_mfma_f32_16x16x32_bf16 v[126:129], v[154:157], v[190:193], v[126:129]
	v_mfma_f32_16x16x32_bf16 v[122:125], v[166:169], v[190:193], v[122:125]
	v_mfma_f32_16x16x32_bf16 v[110:113], v[154:157], v[198:201], v[110:113]
	v_mfma_f32_16x16x32_bf16 v[106:109], v[166:169], v[198:201], v[106:109]
	v_mfma_f32_16x16x32_bf16 v[94:97], v[154:157], v[206:209], v[94:97]
	v_mfma_f32_16x16x32_bf16 v[90:93], v[166:169], v[206:209], v[90:93]
	v_mfma_f32_16x16x32_bf16 v[78:81], v[154:157], v[214:217], v[78:81]
	v_mfma_f32_16x16x32_bf16 v[74:77], v[166:169], v[214:217], v[74:77]
	v_mfma_f32_16x16x32_bf16 v[118:121], v[170:173], v[186:189], v[118:121]
	v_mfma_f32_16x16x32_bf16 v[114:117], v[178:181], v[186:189], v[114:117]
	v_mfma_f32_16x16x32_bf16 v[102:105], v[170:173], v[194:197], v[102:105]
	v_mfma_f32_16x16x32_bf16 v[98:101], v[178:181], v[194:197], v[98:101]
	v_mfma_f32_16x16x32_bf16 v[86:89], v[170:173], v[202:205], v[86:89]
	v_mfma_f32_16x16x32_bf16 v[82:85], v[178:181], v[202:205], v[82:85]
	v_mfma_f32_16x16x32_bf16 v[70:73], v[170:173], v[210:213], v[70:73]
	v_mfma_f32_16x16x32_bf16 v[66:69], v[178:181], v[210:213], v[66:69]
	v_mfma_f32_16x16x32_bf16 v[118:121], v[174:177], v[190:193], v[118:121]
	v_mfma_f32_16x16x32_bf16 v[114:117], v[182:185], v[190:193], v[114:117]
	v_mfma_f32_16x16x32_bf16 v[102:105], v[174:177], v[198:201], v[102:105]
	v_mfma_f32_16x16x32_bf16 v[98:101], v[182:185], v[198:201], v[98:101]
	v_mfma_f32_16x16x32_bf16 v[86:89], v[174:177], v[206:209], v[86:89]
	v_mfma_f32_16x16x32_bf16 v[82:85], v[182:185], v[206:209], v[82:85]
	v_mfma_f32_16x16x32_bf16 v[70:73], v[174:177], v[214:217], v[70:73]
	v_mfma_f32_16x16x32_bf16 v[66:69], v[182:185], v[214:217], v[66:69]
	s_barrier
	s_add_i32 s52, s46, s2
	v_lshl_add_u64 v[162:163], s[30:31], 0, v[132:133]
	s_mov_b32 m0, s52
	ds_read_b128 v[186:189], v151 offset:16384
	ds_read_b128 v[190:193], v151 offset:17408
	ds_read_b128 v[194:197], v151 offset:18432
	ds_read_b128 v[198:201], v151 offset:19456
	ds_read_b128 v[202:205], v151 offset:20480
	ds_read_b128 v[206:209], v151 offset:21504
	ds_read_b128 v[210:213], v151 offset:22528
	ds_read_b128 v[214:217], v151 offset:23552
	global_load_lds_dwordx4 v[162:163], off
	s_add_i32 m0, s52, 0x2000
	s_add_u32 s52, s30, 0x20000
	v_lshl_add_u64 v[218:219], s[30:31], 0, v[136:137]
	s_addc_u32 s53, s31, 0
	s_add_i32 s54, s47, s2
	global_load_lds_dwordx4 v[218:219], off
	v_lshl_add_u64 v[220:221], s[52:53], 0, v[132:133]
	s_mov_b32 m0, s54
	v_lshl_add_u64 v[222:223], s[34:35], 0, v[134:135]
	global_load_lds_dwordx4 v[220:221], off
	v_lshl_add_u64 v[220:221], s[52:53], 0, v[136:137]
	s_add_i32 m0, s54, 0x2000
	s_nop 0
	global_load_lds_dwordx4 v[220:221], off
	v_lshl_add_u64 v[220:221], s[34:35], 0, v[130:131]
	s_waitcnt vmcnt(6)
	s_waitcnt lgkmcnt(0)
	s_barrier
	v_mfma_f32_16x16x32_bf16 v[62:65], v[142:145], v[186:189], v[62:65]
	v_mfma_f32_16x16x32_bf16 v[58:61], v[158:161], v[186:189], v[58:61]
	v_mfma_f32_16x16x32_bf16 v[46:49], v[142:145], v[194:197], v[46:49]
	v_mfma_f32_16x16x32_bf16 v[42:45], v[158:161], v[194:197], v[42:45]
	v_mfma_f32_16x16x32_bf16 v[30:33], v[142:145], v[202:205], v[30:33]
	v_mfma_f32_16x16x32_bf16 v[26:29], v[158:161], v[202:205], v[26:29]
	v_mfma_f32_16x16x32_bf16 v[14:17], v[142:145], v[210:213], v[14:17]
	v_mfma_f32_16x16x32_bf16 v[10:13], v[158:161], v[210:213], v[10:13]
	v_mfma_f32_16x16x32_bf16 v[62:65], v[154:157], v[190:193], v[62:65]
	v_mfma_f32_16x16x32_bf16 v[58:61], v[166:169], v[190:193], v[58:61]
	v_mfma_f32_16x16x32_bf16 v[46:49], v[154:157], v[198:201], v[46:49]
	v_mfma_f32_16x16x32_bf16 v[42:45], v[166:169], v[198:201], v[42:45]
	v_mfma_f32_16x16x32_bf16 v[30:33], v[154:157], v[206:209], v[30:33]
	v_mfma_f32_16x16x32_bf16 v[26:29], v[166:169], v[206:209], v[26:29]
	v_mfma_f32_16x16x32_bf16 v[14:17], v[154:157], v[214:217], v[14:17]
	v_mfma_f32_16x16x32_bf16 v[10:13], v[166:169], v[214:217], v[10:13]
	v_mfma_f32_16x16x32_bf16 v[54:57], v[170:173], v[186:189], v[54:57]
	v_mfma_f32_16x16x32_bf16 v[50:53], v[178:181], v[186:189], v[50:53]
	v_mfma_f32_16x16x32_bf16 v[38:41], v[170:173], v[194:197], v[38:41]
	v_mfma_f32_16x16x32_bf16 v[34:37], v[178:181], v[194:197], v[34:37]
	v_mfma_f32_16x16x32_bf16 v[22:25], v[170:173], v[202:205], v[22:25]
	v_mfma_f32_16x16x32_bf16 v[18:21], v[178:181], v[202:205], v[18:21]
	v_mfma_f32_16x16x32_bf16 v[6:9], v[170:173], v[210:213], v[6:9]
	v_mfma_f32_16x16x32_bf16 v[2:5], v[178:181], v[210:213], v[2:5]
	v_mfma_f32_16x16x32_bf16 v[54:57], v[174:177], v[190:193], v[54:57]
	v_mfma_f32_16x16x32_bf16 v[50:53], v[182:185], v[190:193], v[50:53]
	v_mfma_f32_16x16x32_bf16 v[38:41], v[174:177], v[198:201], v[38:41]
	v_mfma_f32_16x16x32_bf16 v[34:37], v[182:185], v[198:201], v[34:37]
	v_mfma_f32_16x16x32_bf16 v[22:25], v[174:177], v[206:209], v[22:25]
	v_mfma_f32_16x16x32_bf16 v[18:21], v[182:185], v[206:209], v[18:21]
	v_mfma_f32_16x16x32_bf16 v[6:9], v[174:177], v[214:217], v[6:9]
	v_mfma_f32_16x16x32_bf16 v[2:5], v[182:185], v[214:217], v[2:5]
	s_barrier
	s_mov_b32 m0, s27
	s_nop 0
	global_load_lds_dwordx4 v[220:221], off
	s_mov_b32 m0, s37
	s_nop 0
	global_load_lds_dwordx4 v[222:223], off
	s_add_i32 s52, 0, 0x18000
	v_add_u32_e32 v153, s52, v148
	s_add_i32 s53, 0, 0x1c000
	ds_read_b128 v[142:145], v153
	ds_read_b128 v[154:157], v153 offset:1024
	ds_read_b128 v[158:161], v153 offset:2048
	ds_read_b128 v[166:169], v153 offset:3072
	v_add_u32_e32 v153, s53, v148
	ds_read_b128 v[170:173], v153
	ds_read_b128 v[174:177], v153 offset:1024
	ds_read_b128 v[178:181], v153 offset:2048
	ds_read_b128 v[182:185], v153 offset:3072
	s_add_u32 s34, s34, 0x20000
	s_addc_u32 s35, s35, 0
	s_mov_b32 m0, s38
	v_lshl_add_u64 v[224:225], s[34:35], 0, v[130:131]
	ds_read_b128 v[186:189], v151 offset:32768
	ds_read_b128 v[190:193], v151 offset:33792
	ds_read_b128 v[194:197], v151 offset:34816
	ds_read_b128 v[198:201], v151 offset:35840
	ds_read_b128 v[202:205], v151 offset:36864
	ds_read_b128 v[206:209], v151 offset:37888
	ds_read_b128 v[210:213], v151 offset:38912
	ds_read_b128 v[214:217], v151 offset:39936
	global_load_lds_dwordx4 v[224:225], off
	v_lshl_add_u64 v[224:225], s[34:35], 0, v[134:135]
	s_mov_b32 m0, s39
	s_nop 0
	global_load_lds_dwordx4 v[224:225], off
	s_waitcnt vmcnt(8)
	s_waitcnt lgkmcnt(0)
	s_barrier
	v_mfma_f32_16x16x32_bf16 v[126:129], v[142:145], v[186:189], v[126:129]
	v_mfma_f32_16x16x32_bf16 v[122:125], v[158:161], v[186:189], v[122:125]
	v_mfma_f32_16x16x32_bf16 v[110:113], v[142:145], v[194:197], v[110:113]
	v_mfma_f32_16x16x32_bf16 v[106:109], v[158:161], v[194:197], v[106:109]
	v_mfma_f32_16x16x32_bf16 v[94:97], v[142:145], v[202:205], v[94:97]
	v_mfma_f32_16x16x32_bf16 v[90:93], v[158:161], v[202:205], v[90:93]
	v_mfma_f32_16x16x32_bf16 v[78:81], v[142:145], v[210:213], v[78:81]
	v_mfma_f32_16x16x32_bf16 v[74:77], v[158:161], v[210:213], v[74:77]
	v_mfma_f32_16x16x32_bf16 v[126:129], v[154:157], v[190:193], v[126:129]
	v_mfma_f32_16x16x32_bf16 v[122:125], v[166:169], v[190:193], v[122:125]
	v_mfma_f32_16x16x32_bf16 v[110:113], v[154:157], v[198:201], v[110:113]
	v_mfma_f32_16x16x32_bf16 v[106:109], v[166:169], v[198:201], v[106:109]
	v_mfma_f32_16x16x32_bf16 v[94:97], v[154:157], v[206:209], v[94:97]
	v_mfma_f32_16x16x32_bf16 v[90:93], v[166:169], v[206:209], v[90:93]
	v_mfma_f32_16x16x32_bf16 v[78:81], v[154:157], v[214:217], v[78:81]
	v_mfma_f32_16x16x32_bf16 v[74:77], v[166:169], v[214:217], v[74:77]
	v_mfma_f32_16x16x32_bf16 v[118:121], v[170:173], v[186:189], v[118:121]
	v_mfma_f32_16x16x32_bf16 v[114:117], v[178:181], v[186:189], v[114:117]
	v_mfma_f32_16x16x32_bf16 v[102:105], v[170:173], v[194:197], v[102:105]
	v_mfma_f32_16x16x32_bf16 v[98:101], v[178:181], v[194:197], v[98:101]
	v_mfma_f32_16x16x32_bf16 v[86:89], v[170:173], v[202:205], v[86:89]
	v_mfma_f32_16x16x32_bf16 v[82:85], v[178:181], v[202:205], v[82:85]
	v_mfma_f32_16x16x32_bf16 v[70:73], v[170:173], v[210:213], v[70:73]
	v_mfma_f32_16x16x32_bf16 v[66:69], v[178:181], v[210:213], v[66:69]
	v_mfma_f32_16x16x32_bf16 v[118:121], v[174:177], v[190:193], v[118:121]
	v_mfma_f32_16x16x32_bf16 v[114:117], v[182:185], v[190:193], v[114:117]
	v_mfma_f32_16x16x32_bf16 v[102:105], v[174:177], v[198:201], v[102:105]
	v_mfma_f32_16x16x32_bf16 v[98:101], v[182:185], v[198:201], v[98:101]
	v_mfma_f32_16x16x32_bf16 v[86:89], v[174:177], v[206:209], v[86:89]
	v_mfma_f32_16x16x32_bf16 v[82:85], v[182:185], v[206:209], v[82:85]
	v_mfma_f32_16x16x32_bf16 v[70:73], v[174:177], v[214:217], v[70:73]
	v_mfma_f32_16x16x32_bf16 v[66:69], v[182:185], v[214:217], v[66:69]
	s_barrier
	s_add_i32 s34, s52, s2
	v_lshl_add_u64 v[162:163], v[162:163], 0, s[10:11]
	s_mov_b32 m0, s34
	ds_read_b128 v[186:189], v151 offset:49152
	ds_read_b128 v[190:193], v151 offset:50176
	ds_read_b128 v[194:197], v151 offset:51200
	ds_read_b128 v[198:201], v151 offset:52224
	ds_read_b128 v[202:205], v151 offset:53248
	ds_read_b128 v[206:209], v151 offset:54272
	ds_read_b128 v[210:213], v151 offset:55296
	ds_read_b128 v[214:217], v151 offset:56320
	global_load_lds_dwordx4 v[162:163], off
	s_add_i32 m0, s34, 0x2000
	s_add_u32 s30, s30, 0x20080
	v_lshl_add_u64 v[162:163], v[218:219], 0, s[10:11]
	s_addc_u32 s31, s31, 0
	s_add_i32 s34, s53, s2
	global_load_lds_dwordx4 v[162:163], off
	v_lshl_add_u64 v[162:163], s[30:31], 0, v[132:133]
	s_mov_b32 m0, s34
	s_nop 0
	global_load_lds_dwordx4 v[162:163], off
	v_lshl_add_u64 v[162:163], s[30:31], 0, v[136:137]
	s_add_i32 m0, s34, 0x2000
	s_nop 0
	global_load_lds_dwordx4 v[162:163], off
	s_waitcnt vmcnt(6)
	s_waitcnt lgkmcnt(0)
	s_barrier
	v_mfma_f32_16x16x32_bf16 v[62:65], v[142:145], v[186:189], v[62:65]
	v_mfma_f32_16x16x32_bf16 v[58:61], v[158:161], v[186:189], v[58:61]
	v_mfma_f32_16x16x32_bf16 v[46:49], v[142:145], v[194:197], v[46:49]
	v_mfma_f32_16x16x32_bf16 v[42:45], v[158:161], v[194:197], v[42:45]
	v_mfma_f32_16x16x32_bf16 v[30:33], v[142:145], v[202:205], v[30:33]
	v_mfma_f32_16x16x32_bf16 v[26:29], v[158:161], v[202:205], v[26:29]
	v_mfma_f32_16x16x32_bf16 v[14:17], v[142:145], v[210:213], v[14:17]
	v_mfma_f32_16x16x32_bf16 v[10:13], v[158:161], v[210:213], v[10:13]
	v_mfma_f32_16x16x32_bf16 v[62:65], v[154:157], v[190:193], v[62:65]
	v_mfma_f32_16x16x32_bf16 v[58:61], v[166:169], v[190:193], v[58:61]
	v_mfma_f32_16x16x32_bf16 v[46:49], v[154:157], v[198:201], v[46:49]
	v_mfma_f32_16x16x32_bf16 v[42:45], v[166:169], v[198:201], v[42:45]
	v_mfma_f32_16x16x32_bf16 v[30:33], v[154:157], v[206:209], v[30:33]
	v_mfma_f32_16x16x32_bf16 v[26:29], v[166:169], v[206:209], v[26:29]
	v_mfma_f32_16x16x32_bf16 v[14:17], v[154:157], v[214:217], v[14:17]
	v_mfma_f32_16x16x32_bf16 v[10:13], v[166:169], v[214:217], v[10:13]
	v_mfma_f32_16x16x32_bf16 v[54:57], v[170:173], v[186:189], v[54:57]
	v_mfma_f32_16x16x32_bf16 v[50:53], v[178:181], v[186:189], v[50:53]
	v_mfma_f32_16x16x32_bf16 v[38:41], v[170:173], v[194:197], v[38:41]
	v_mfma_f32_16x16x32_bf16 v[34:37], v[178:181], v[194:197], v[34:37]
	v_mfma_f32_16x16x32_bf16 v[22:25], v[170:173], v[202:205], v[22:25]
	v_mfma_f32_16x16x32_bf16 v[18:21], v[178:181], v[202:205], v[18:21]
	v_mfma_f32_16x16x32_bf16 v[6:9], v[170:173], v[210:213], v[6:9]
	v_mfma_f32_16x16x32_bf16 v[2:5], v[178:181], v[210:213], v[2:5]
	v_mfma_f32_16x16x32_bf16 v[54:57], v[174:177], v[190:193], v[54:57]
	v_mfma_f32_16x16x32_bf16 v[50:53], v[182:185], v[190:193], v[50:53]
	v_mfma_f32_16x16x32_bf16 v[38:41], v[174:177], v[198:201], v[38:41]
	v_mfma_f32_16x16x32_bf16 v[34:37], v[182:185], v[198:201], v[34:37]
	v_mfma_f32_16x16x32_bf16 v[22:25], v[174:177], v[206:209], v[22:25]
	v_mfma_f32_16x16x32_bf16 v[18:21], v[182:185], v[206:209], v[18:21]
	v_mfma_f32_16x16x32_bf16 v[6:9], v[174:177], v[214:217], v[6:9]
	v_mfma_f32_16x16x32_bf16 v[2:5], v[182:185], v[214:217], v[2:5]
	s_barrier
	s_add_i32 s51, s51, 2
	s_add_u32 s28, s28, 0x100
	s_addc_u32 s29, s29, 0
	s_add_u32 s49, s49, 0x100
	s_addc_u32 s50, s50, 0
	s_cmp_gt_u32 s51, 5
	s_cbranch_scc0 .Lkback_1220
	v_lshl_add_u64 v[244:245], v[220:221], 0, s[10:11]
	s_mov_b32 m0, s43
	s_nop 0
	global_load_lds_dwordx4 v[244:245], off
	v_lshl_add_u64 v[244:245], v[222:223], 0, s[10:11]
	s_mov_b32 m0, s44
	s_nop 0
	global_load_lds_dwordx4 v[244:245], off
	s_setprio 0
	s_lshl_b32 s98, s26, 8
	s_add_i32 s98, s98, s41
	v_add_u32_e32 v240, s98, v146
	s_lshl_b32 s98, s0, 8
	s_or_b32 s98, s98, s42
	v_lshl_add_u32 v241, v147, 3, s98
	v_lshlrev_b32_e32 v240, 12, v240
	v_lshl_add_u32 v240, v241, 1, v240
	global_load_dwordx4 v[168:171], v240, s[62:63]
	global_load_dwordx4 v[172:175], v240, s[62:63] offset:256
	v_add_u32_e32 v240, 0x10000, v240
	global_load_dwordx4 v[176:179], v240, s[62:63]
	global_load_dwordx4 v[180:183], v240, s[62:63] offset:256
	v_add_u32_e32 v240, 0x10000, v240
	global_load_dwordx4 v[184:187], v240, s[62:63]
	global_load_dwordx4 v[188:191], v240, s[62:63] offset:256
	v_add_u32_e32 v240, 0x10000, v240
	global_load_dwordx4 v[192:195], v240, s[62:63]
	global_load_dwordx4 v[196:199], v240, s[62:63] offset:256
	v_add_u32_e32 v240, 0x50000, v240
	global_load_dwordx4 v[200:203], v240, s[62:63]
	global_load_dwordx4 v[204:207], v240, s[62:63] offset:256
	v_add_u32_e32 v240, 0x10000, v240
	global_load_dwordx4 v[208:211], v240, s[62:63]
	global_load_dwordx4 v[212:215], v240, s[62:63] offset:256
	v_add_u32_e32 v240, 0x10000, v240
	global_load_dwordx4 v[216:219], v240, s[62:63]
	global_load_dwordx4 v[220:223], v240, s[62:63] offset:256
	v_add_u32_e32 v240, 0x10000, v240
	global_load_dwordx4 v[224:227], v240, s[62:63]
	global_load_dwordx4 v[232:235], v240, s[62:63] offset:256
	s_and_b64 vcc, exec, s[12:13]
	s_cbranch_vccz .LBB0_1223
	s_barrier

.LBB0_1336:
	s_and_b64 s[34:35], s[0:1], exec
	s_cselect_b32 s17, s21, s29
	s_cselect_b32 s19, s20, s28
	s_cselect_b32 s50, s23, s31
	s_cselect_b32 s51, s22, s30
	s_add_u32 s28, s28, 0x80080
	s_addc_u32 s29, s29, 0
	s_add_u32 s52, s30, 0x100
	v_mov_b32_e32 v6, 0
	s_addc_u32 s53, s31, 0
	s_mov_b32 s54, -2
	v_mov_b32_e32 v7, v6
	v_mov_b32_e32 v8, v6
	v_mov_b32_e32 v9, v6
	v_mov_b32_e32 v14, v6
	v_mov_b32_e32 v15, v6
	v_mov_b32_e32 v16, v6
	v_mov_b32_e32 v17, v6
	v_mov_b32_e32 v22, v6
	v_mov_b32_e32 v23, v6
	v_mov_b32_e32 v24, v6
	v_mov_b32_e32 v25, v6
	v_mov_b32_e32 v30, v6
	v_mov_b32_e32 v31, v6
	v_mov_b32_e32 v32, v6
	v_mov_b32_e32 v33, v6
	v_mov_b32_e32 v38, v6
	v_mov_b32_e32 v39, v6
	v_mov_b32_e32 v40, v6
	v_mov_b32_e32 v41, v6
	v_mov_b32_e32 v46, v6
	v_mov_b32_e32 v47, v6
	v_mov_b32_e32 v48, v6
	v_mov_b32_e32 v49, v6
	v_mov_b32_e32 v54, v6
	v_mov_b32_e32 v55, v6
	v_mov_b32_e32 v56, v6
	v_mov_b32_e32 v57, v6
	v_mov_b32_e32 v62, v6
	v_mov_b32_e32 v63, v6
	v_mov_b32_e32 v64, v6
	v_mov_b32_e32 v65, v6
	v_mov_b32_e32 v2, v6
	v_mov_b32_e32 v3, v6
	v_mov_b32_e32 v4, v6
	v_mov_b32_e32 v5, v6
	v_mov_b32_e32 v10, v6
	v_mov_b32_e32 v11, v6
	v_mov_b32_e32 v12, v6
	v_mov_b32_e32 v13, v6
	v_mov_b32_e32 v18, v6
	v_mov_b32_e32 v19, v6
	v_mov_b32_e32 v20, v6
	v_mov_b32_e32 v21, v6
	v_mov_b32_e32 v26, v6
	v_mov_b32_e32 v27, v6
	v_mov_b32_e32 v28, v6
	v_mov_b32_e32 v29, v6
	v_mov_b32_e32 v34, v6
	v_mov_b32_e32 v35, v6
	v_mov_b32_e32 v36, v6
	v_mov_b32_e32 v37, v6
	v_mov_b32_e32 v42, v6
	v_mov_b32_e32 v43, v6
	v_mov_b32_e32 v44, v6
	v_mov_b32_e32 v45, v6
	v_mov_b32_e32 v50, v6
	v_mov_b32_e32 v51, v6
	v_mov_b32_e32 v52, v6
	v_mov_b32_e32 v53, v6
	v_mov_b32_e32 v58, v6
	v_mov_b32_e32 v59, v6
	v_mov_b32_e32 v60, v6
	v_mov_b32_e32 v61, v6
	v_mov_b32_e32 v70, v6
	v_mov_b32_e32 v71, v6
	v_mov_b32_e32 v72, v6
	v_mov_b32_e32 v73, v6
	v_mov_b32_e32 v78, v6
	v_mov_b32_e32 v79, v6
	v_mov_b32_e32 v80, v6
	v_mov_b32_e32 v81, v6
	v_mov_b32_e32 v86, v6
	v_mov_b32_e32 v87, v6
	v_mov_b32_e32 v88, v6
	v_mov_b32_e32 v89, v6
	v_mov_b32_e32 v94, v6
	v_mov_b32_e32 v95, v6
	v_mov_b32_e32 v96, v6
	v_mov_b32_e32 v97, v6
	v_mov_b32_e32 v102, v6
	v_mov_b32_e32 v103, v6
	v_mov_b32_e32 v104, v6
	v_mov_b32_e32 v105, v6
	v_mov_b32_e32 v110, v6
	v_mov_b32_e32 v111, v6
	v_mov_b32_e32 v112, v6
	v_mov_b32_e32 v113, v6
	v_mov_b32_e32 v118, v6
	v_mov_b32_e32 v119, v6
	v_mov_b32_e32 v120, v6
	v_mov_b32_e32 v121, v6
	v_mov_b32_e32 v126, v6
	v_mov_b32_e32 v127, v6
	v_mov_b32_e32 v128, v6
	v_mov_b32_e32 v129, v6
	v_mov_b32_e32 v66, v6
	v_mov_b32_e32 v67, v6
	v_mov_b32_e32 v68, v6
	v_mov_b32_e32 v69, v6
	v_mov_b32_e32 v74, v6
	v_mov_b32_e32 v75, v6
	v_mov_b32_e32 v76, v6
	v_mov_b32_e32 v77, v6
	v_mov_b32_e32 v82, v6
	v_mov_b32_e32 v83, v6
	v_mov_b32_e32 v84, v6
	v_mov_b32_e32 v85, v6
	v_mov_b32_e32 v90, v6
	v_mov_b32_e32 v91, v6
	v_mov_b32_e32 v92, v6
	v_mov_b32_e32 v93, v6
	v_mov_b32_e32 v98, v6
	v_mov_b32_e32 v99, v6
	v_mov_b32_e32 v100, v6
	v_mov_b32_e32 v101, v6
	v_mov_b32_e32 v106, v6
	v_mov_b32_e32 v107, v6
	v_mov_b32_e32 v108, v6
	v_mov_b32_e32 v109, v6
	v_mov_b32_e32 v114, v6
	v_mov_b32_e32 v115, v6
	v_mov_b32_e32 v116, v6
	v_mov_b32_e32 v117, v6
	v_mov_b32_e32 v122, v6
	v_mov_b32_e32 v123, v6
	v_mov_b32_e32 v124, v6
	v_mov_b32_e32 v125, v6
	s_and_b64 vcc, exec, s[8:9]
	s_cbranch_vccz .Lsp_p10
	s_setprio 1
.Lsp_p10:
	s_branch .LBB0_1337
.Lkback_1337:
	v_lshl_add_u64 v[244:245], v[220:221], 0, s[12:13]
	s_mov_b32 m0, s42
	s_nop 0
	global_load_lds_dwordx4 v[244:245], off
	v_lshl_add_u64 v[244:245], v[222:223], 0, s[12:13]
	s_mov_b32 m0, s43
	s_nop 0
	global_load_lds_dwordx4 v[244:245], off
.LBB0_1337:
	ds_read_b128 v[142:145], v149
	ds_read_b128 v[154:157], v149 offset:1024
	ds_read_b128 v[158:161], v149 offset:2048
	ds_read_b128 v[166:169], v149 offset:3072
	ds_read_b128 v[170:173], v150
	ds_read_b128 v[174:177], v150 offset:1024
	ds_read_b128 v[178:181], v150 offset:2048
	ds_read_b128 v[182:185], v150 offset:3072
	s_add_u32 s30, s28, 0xfff80080
	s_addc_u32 s31, s29, -1
	s_cmp_eq_u32 s54, 28
	s_cselect_b32 s35, s17, s31
	s_cselect_b32 s34, s19, s30
	s_cselect_b32 s31, s50, s53
	s_cselect_b32 s30, s51, s52
	v_lshl_add_u64 v[162:163], s[28:29], 0, v[138:139]
	s_add_i32 m0, s25, 0xc000
	ds_read_b128 v[186:189], v151
	ds_read_b128 v[190:193], v151 offset:1024
	ds_read_b128 v[194:197], v151 offset:2048
	ds_read_b128 v[198:201], v151 offset:3072
	ds_read_b128 v[202:205], v151 offset:4096
	ds_read_b128 v[206:209], v151 offset:5120
	ds_read_b128 v[210:213], v151 offset:6144
	ds_read_b128 v[214:217], v151 offset:7168
	global_load_lds_dwordx4 v[162:163], off
	v_lshl_add_u64 v[162:163], s[28:29], 0, v[140:141]
	s_add_i32 m0, s25, 0xe000
	s_nop 0
	global_load_lds_dwordx4 v[162:163], off
	s_waitcnt vmcnt(8)
	s_waitcnt lgkmcnt(0)
	s_barrier
	v_mfma_f32_16x16x32_bf16 v[122:125], v[142:145], v[186:189], v[122:125]
	v_mfma_f32_16x16x32_bf16 v[114:117], v[158:161], v[186:189], v[114:117]
	v_mfma_f32_16x16x32_bf16 v[106:109], v[142:145], v[194:197], v[106:109]
	v_mfma_f32_16x16x32_bf16 v[98:101], v[158:161], v[194:197], v[98:101]
	v_mfma_f32_16x16x32_bf16 v[90:93], v[142:145], v[202:205], v[90:93]
	v_mfma_f32_16x16x32_bf16 v[82:85], v[158:161], v[202:205], v[82:85]
	v_mfma_f32_16x16x32_bf16 v[74:77], v[142:145], v[210:213], v[74:77]
	v_mfma_f32_16x16x32_bf16 v[66:69], v[158:161], v[210:213], v[66:69]
	v_mfma_f32_16x16x32_bf16 v[122:125], v[154:157], v[190:193], v[122:125]
	v_mfma_f32_16x16x32_bf16 v[114:117], v[166:169], v[190:193], v[114:117]
	v_mfma_f32_16x16x32_bf16 v[106:109], v[154:157], v[198:201], v[106:109]
	v_mfma_f32_16x16x32_bf16 v[98:101], v[166:169], v[198:201], v[98:101]
	v_mfma_f32_16x16x32_bf16 v[90:93], v[154:157], v[206:209], v[90:93]
	v_mfma_f32_16x16x32_bf16 v[82:85], v[166:169], v[206:209], v[82:85]
	v_mfma_f32_16x16x32_bf16 v[74:77], v[154:157], v[214:217], v[74:77]
	v_mfma_f32_16x16x32_bf16 v[66:69], v[166:169], v[214:217], v[66:69]
	v_mfma_f32_16x16x32_bf16 v[126:129], v[170:173], v[186:189], v[126:129]
	v_mfma_f32_16x16x32_bf16 v[118:121], v[178:181], v[186:189], v[118:121]
	v_mfma_f32_16x16x32_bf16 v[110:113], v[170:173], v[194:197], v[110:113]
	v_mfma_f32_16x16x32_bf16 v[102:105], v[178:181], v[194:197], v[102:105]
	v_mfma_f32_16x16x32_bf16 v[94:97], v[170:173], v[202:205], v[94:97]
	v_mfma_f32_16x16x32_bf16 v[86:89], v[178:181], v[202:205], v[86:89]
	v_mfma_f32_16x16x32_bf16 v[78:81], v[170:173], v[210:213], v[78:81]
	v_mfma_f32_16x16x32_bf16 v[70:73], v[178:181], v[210:213], v[70:73]
	v_mfma_f32_16x16x32_bf16 v[126:129], v[174:177], v[190:193], v[126:129]
	v_mfma_f32_16x16x32_bf16 v[118:121], v[182:185], v[190:193], v[118:121]
	v_mfma_f32_16x16x32_bf16 v[110:113], v[174:177], v[198:201], v[110:113]
	v_mfma_f32_16x16x32_bf16 v[102:105], v[182:185], v[198:201], v[102:105]
	v_mfma_f32_16x16x32_bf16 v[94:97], v[174:177], v[206:209], v[94:97]
	v_mfma_f32_16x16x32_bf16 v[86:89], v[182:185], v[206:209], v[86:89]
	v_mfma_f32_16x16x32_bf16 v[78:81], v[174:177], v[214:217], v[78:81]
	v_mfma_f32_16x16x32_bf16 v[70:73], v[182:185], v[214:217], v[70:73]
	s_barrier
	s_add_i32 s55, s46, s36
	v_lshl_add_u64 v[162:163], s[30:31], 0, v[132:133]
	s_mov_b32 m0, s55
	ds_read_b128 v[186:189], v151 offset:16384
	ds_read_b128 v[190:193], v151 offset:17408
	ds_read_b128 v[194:197], v151 offset:18432
	ds_read_b128 v[198:201], v151 offset:19456
	ds_read_b128 v[202:205], v151 offset:20480
	ds_read_b128 v[206:209], v151 offset:21504
	ds_read_b128 v[210:213], v151 offset:22528
	ds_read_b128 v[214:217], v151 offset:23552
	global_load_lds_dwordx4 v[162:163], off
	s_add_i32 m0, s55, 0x2000
	s_add_u32 s56, s30, 0x80000
	v_lshl_add_u64 v[218:219], s[30:31], 0, v[136:137]
	s_addc_u32 s57, s31, 0
	s_add_i32 s55, s47, s36
	global_load_lds_dwordx4 v[218:219], off
	v_lshl_add_u64 v[220:221], s[56:57], 0, v[132:133]
	s_mov_b32 m0, s55
	v_lshl_add_u64 v[222:223], s[34:35], 0, v[134:135]
	global_load_lds_dwordx4 v[220:221], off
	v_lshl_add_u64 v[220:221], s[56:57], 0, v[136:137]
	s_add_i32 m0, s55, 0x2000
	s_nop 0
	global_load_lds_dwordx4 v[220:221], off
	v_lshl_add_u64 v[220:221], s[34:35], 0, v[130:131]
	s_waitcnt vmcnt(6)
	s_waitcnt lgkmcnt(0)
	s_barrier
	v_mfma_f32_16x16x32_bf16 v[58:61], v[142:145], v[186:189], v[58:61]
	v_mfma_f32_16x16x32_bf16 v[50:53], v[158:161], v[186:189], v[50:53]
	v_mfma_f32_16x16x32_bf16 v[42:45], v[142:145], v[194:197], v[42:45]
	v_mfma_f32_16x16x32_bf16 v[34:37], v[158:161], v[194:197], v[34:37]
	v_mfma_f32_16x16x32_bf16 v[26:29], v[142:145], v[202:205], v[26:29]
	v_mfma_f32_16x16x32_bf16 v[18:21], v[158:161], v[202:205], v[18:21]
	v_mfma_f32_16x16x32_bf16 v[10:13], v[142:145], v[210:213], v[10:13]
	v_mfma_f32_16x16x32_bf16 v[2:5], v[158:161], v[210:213], v[2:5]
	v_mfma_f32_16x16x32_bf16 v[58:61], v[154:157], v[190:193], v[58:61]
	v_mfma_f32_16x16x32_bf16 v[50:53], v[166:169], v[190:193], v[50:53]
	v_mfma_f32_16x16x32_bf16 v[42:45], v[154:157], v[198:201], v[42:45]
	v_mfma_f32_16x16x32_bf16 v[34:37], v[166:169], v[198:201], v[34:37]
	v_mfma_f32_16x16x32_bf16 v[26:29], v[154:157], v[206:209], v[26:29]
	v_mfma_f32_16x16x32_bf16 v[18:21], v[166:169], v[206:209], v[18:21]
	v_mfma_f32_16x16x32_bf16 v[10:13], v[154:157], v[214:217], v[10:13]
	v_mfma_f32_16x16x32_bf16 v[2:5], v[166:169], v[214:217], v[2:5]
	v_mfma_f32_16x16x32_bf16 v[62:65], v[170:173], v[186:189], v[62:65]
	v_mfma_f32_16x16x32_bf16 v[54:57], v[178:181], v[186:189], v[54:57]
	v_mfma_f32_16x16x32_bf16 v[46:49], v[170:173], v[194:197], v[46:49]
	v_mfma_f32_16x16x32_bf16 v[38:41], v[178:181], v[194:197], v[38:41]
	v_mfma_f32_16x16x32_bf16 v[30:33], v[170:173], v[202:205], v[30:33]
	v_mfma_f32_16x16x32_bf16 v[22:25], v[178:181], v[202:205], v[22:25]
	v_mfma_f32_16x16x32_bf16 v[14:17], v[170:173], v[210:213], v[14:17]
	v_mfma_f32_16x16x32_bf16 v[6:9], v[178:181], v[210:213], v[6:9]
	v_mfma_f32_16x16x32_bf16 v[62:65], v[174:177], v[190:193], v[62:65]
	v_mfma_f32_16x16x32_bf16 v[54:57], v[182:185], v[190:193], v[54:57]
	v_mfma_f32_16x16x32_bf16 v[46:49], v[174:177], v[198:201], v[46:49]
	v_mfma_f32_16x16x32_bf16 v[38:41], v[182:185], v[198:201], v[38:41]
	v_mfma_f32_16x16x32_bf16 v[30:33], v[174:177], v[206:209], v[30:33]
	v_mfma_f32_16x16x32_bf16 v[22:25], v[182:185], v[206:209], v[22:25]
	v_mfma_f32_16x16x32_bf16 v[14:17], v[174:177], v[214:217], v[14:17]
	v_mfma_f32_16x16x32_bf16 v[6:9], v[182:185], v[214:217], v[6:9]
	s_barrier
	s_mov_b32 m0, s25
	s_nop 0
	global_load_lds_dwordx4 v[220:221], off
	s_mov_b32 m0, s27
	s_nop 0
	global_load_lds_dwordx4 v[222:223], off
	s_add_i32 s55, 0, 0x18000
	v_add_u32_e32 v153, s55, v148
	s_add_i32 s56, 0, 0x1c000
	ds_read_b128 v[142:145], v153
	ds_read_b128 v[154:157], v153 offset:1024
	ds_read_b128 v[158:161], v153 offset:2048
	ds_read_b128 v[166:169], v153 offset:3072
	v_add_u32_e32 v153, s56, v148
	ds_read_b128 v[170:173], v153
	ds_read_b128 v[174:177], v153 offset:1024
	ds_read_b128 v[178:181], v153 offset:2048
	ds_read_b128 v[182:185], v153 offset:3072
	s_add_u32 s34, s34, 0x80000
	s_addc_u32 s35, s35, 0
	s_mov_b32 m0, s37
	v_lshl_add_u64 v[224:225], s[34:35], 0, v[130:131]
	ds_read_b128 v[186:189], v151 offset:32768
	ds_read_b128 v[190:193], v151 offset:33792
	ds_read_b128 v[194:197], v151 offset:34816
	ds_read_b128 v[198:201], v151 offset:35840
	ds_read_b128 v[202:205], v151 offset:36864
	ds_read_b128 v[206:209], v151 offset:37888
	ds_read_b128 v[210:213], v151 offset:38912
	ds_read_b128 v[214:217], v151 offset:39936
	global_load_lds_dwordx4 v[224:225], off
	v_lshl_add_u64 v[224:225], s[34:35], 0, v[134:135]
	s_mov_b32 m0, s38
	s_nop 0
	global_load_lds_dwordx4 v[224:225], off
	s_waitcnt vmcnt(8)
	s_waitcnt lgkmcnt(0)
	s_barrier
	v_mfma_f32_16x16x32_bf16 v[122:125], v[142:145], v[186:189], v[122:125]
	v_mfma_f32_16x16x32_bf16 v[114:117], v[158:161], v[186:189], v[114:117]
	v_mfma_f32_16x16x32_bf16 v[106:109], v[142:145], v[194:197], v[106:109]
	v_mfma_f32_16x16x32_bf16 v[98:101], v[158:161], v[194:197], v[98:101]
	v_mfma_f32_16x16x32_bf16 v[90:93], v[142:145], v[202:205], v[90:93]
	v_mfma_f32_16x16x32_bf16 v[82:85], v[158:161], v[202:205], v[82:85]
	v_mfma_f32_16x16x32_bf16 v[74:77], v[142:145], v[210:213], v[74:77]
	v_mfma_f32_16x16x32_bf16 v[66:69], v[158:161], v[210:213], v[66:69]
	v_mfma_f32_16x16x32_bf16 v[122:125], v[154:157], v[190:193], v[122:125]
	v_mfma_f32_16x16x32_bf16 v[114:117], v[166:169], v[190:193], v[114:117]
	v_mfma_f32_16x16x32_bf16 v[106:109], v[154:157], v[198:201], v[106:109]
	v_mfma_f32_16x16x32_bf16 v[98:101], v[166:169], v[198:201], v[98:101]
	v_mfma_f32_16x16x32_bf16 v[90:93], v[154:157], v[206:209], v[90:93]
	v_mfma_f32_16x16x32_bf16 v[82:85], v[166:169], v[206:209], v[82:85]
	v_mfma_f32_16x16x32_bf16 v[74:77], v[154:157], v[214:217], v[74:77]
	v_mfma_f32_16x16x32_bf16 v[66:69], v[166:169], v[214:217], v[66:69]
	v_mfma_f32_16x16x32_bf16 v[126:129], v[170:173], v[186:189], v[126:129]
	v_mfma_f32_16x16x32_bf16 v[118:121], v[178:181], v[186:189], v[118:121]
	v_mfma_f32_16x16x32_bf16 v[110:113], v[170:173], v[194:197], v[110:113]
	v_mfma_f32_16x16x32_bf16 v[102:105], v[178:181], v[194:197], v[102:105]
	v_mfma_f32_16x16x32_bf16 v[94:97], v[170:173], v[202:205], v[94:97]
	v_mfma_f32_16x16x32_bf16 v[86:89], v[178:181], v[202:205], v[86:89]
	v_mfma_f32_16x16x32_bf16 v[78:81], v[170:173], v[210:213], v[78:81]
	v_mfma_f32_16x16x32_bf16 v[70:73], v[178:181], v[210:213], v[70:73]
	v_mfma_f32_16x16x32_bf16 v[126:129], v[174:177], v[190:193], v[126:129]
	v_mfma_f32_16x16x32_bf16 v[118:121], v[182:185], v[190:193], v[118:121]
	v_mfma_f32_16x16x32_bf16 v[110:113], v[174:177], v[198:201], v[110:113]
	v_mfma_f32_16x16x32_bf16 v[102:105], v[182:185], v[198:201], v[102:105]
	v_mfma_f32_16x16x32_bf16 v[94:97], v[174:177], v[206:209], v[94:97]
	v_mfma_f32_16x16x32_bf16 v[86:89], v[182:185], v[206:209], v[86:89]
	v_mfma_f32_16x16x32_bf16 v[78:81], v[174:177], v[214:217], v[78:81]
	v_mfma_f32_16x16x32_bf16 v[70:73], v[182:185], v[214:217], v[70:73]
	s_barrier
	s_add_i32 s34, s55, s36
	v_lshl_add_u64 v[162:163], v[162:163], 0, s[12:13]
	s_mov_b32 m0, s34
	ds_read_b128 v[186:189], v151 offset:49152
	ds_read_b128 v[190:193], v151 offset:50176
	ds_read_b128 v[194:197], v151 offset:51200
	ds_read_b128 v[198:201], v151 offset:52224
	ds_read_b128 v[202:205], v151 offset:53248
	ds_read_b128 v[206:209], v151 offset:54272
	ds_read_b128 v[210:213], v151 offset:55296
	ds_read_b128 v[214:217], v151 offset:56320
	global_load_lds_dwordx4 v[162:163], off
	s_add_i32 m0, s34, 0x2000
	s_add_u32 s30, s30, 0x80080
	v_lshl_add_u64 v[162:163], v[218:219], 0, s[12:13]
	s_addc_u32 s31, s31, 0
	s_add_i32 s34, s56, s36
	global_load_lds_dwordx4 v[162:163], off
	v_lshl_add_u64 v[162:163], s[30:31], 0, v[132:133]
	s_mov_b32 m0, s34
	s_nop 0
	global_load_lds_dwordx4 v[162:163], off
	v_lshl_add_u64 v[162:163], s[30:31], 0, v[136:137]
	s_add_i32 m0, s34, 0x2000
	s_nop 0
	global_load_lds_dwordx4 v[162:163], off
	s_waitcnt vmcnt(6)
	s_waitcnt lgkmcnt(0)
	s_barrier
	v_mfma_f32_16x16x32_bf16 v[58:61], v[142:145], v[186:189], v[58:61]
	v_mfma_f32_16x16x32_bf16 v[50:53], v[158:161], v[186:189], v[50:53]
	v_mfma_f32_16x16x32_bf16 v[42:45], v[142:145], v[194:197], v[42:45]
	v_mfma_f32_16x16x32_bf16 v[34:37], v[158:161], v[194:197], v[34:37]
	v_mfma_f32_16x16x32_bf16 v[26:29], v[142:145], v[202:205], v[26:29]
	v_mfma_f32_16x16x32_bf16 v[18:21], v[158:161], v[202:205], v[18:21]
	v_mfma_f32_16x16x32_bf16 v[10:13], v[142:145], v[210:213], v[10:13]
	v_mfma_f32_16x16x32_bf16 v[2:5], v[158:161], v[210:213], v[2:5]
	v_mfma_f32_16x16x32_bf16 v[58:61], v[154:157], v[190:193], v[58:61]
	v_mfma_f32_16x16x32_bf16 v[50:53], v[166:169], v[190:193], v[50:53]
	v_mfma_f32_16x16x32_bf16 v[42:45], v[154:157], v[198:201], v[42:45]
	v_mfma_f32_16x16x32_bf16 v[34:37], v[166:169], v[198:201], v[34:37]
	v_mfma_f32_16x16x32_bf16 v[26:29], v[154:157], v[206:209], v[26:29]
	v_mfma_f32_16x16x32_bf16 v[18:21], v[166:169], v[206:209], v[18:21]
	v_mfma_f32_16x16x32_bf16 v[10:13], v[154:157], v[214:217], v[10:13]
	v_mfma_f32_16x16x32_bf16 v[2:5], v[166:169], v[214:217], v[2:5]
	v_mfma_f32_16x16x32_bf16 v[62:65], v[170:173], v[186:189], v[62:65]
	v_mfma_f32_16x16x32_bf16 v[54:57], v[178:181], v[186:189], v[54:57]
	v_mfma_f32_16x16x32_bf16 v[46:49], v[170:173], v[194:197], v[46:49]
	v_mfma_f32_16x16x32_bf16 v[38:41], v[178:181], v[194:197], v[38:41]
	v_mfma_f32_16x16x32_bf16 v[30:33], v[170:173], v[202:205], v[30:33]
	v_mfma_f32_16x16x32_bf16 v[22:25], v[178:181], v[202:205], v[22:25]
	v_mfma_f32_16x16x32_bf16 v[14:17], v[170:173], v[210:213], v[14:17]
	v_mfma_f32_16x16x32_bf16 v[6:9], v[178:181], v[210:213], v[6:9]
	v_mfma_f32_16x16x32_bf16 v[62:65], v[174:177], v[190:193], v[62:65]
	v_mfma_f32_16x16x32_bf16 v[54:57], v[182:185], v[190:193], v[54:57]
	v_mfma_f32_16x16x32_bf16 v[46:49], v[174:177], v[198:201], v[46:49]
	v_mfma_f32_16x16x32_bf16 v[38:41], v[182:185], v[198:201], v[38:41]
	v_mfma_f32_16x16x32_bf16 v[30:33], v[174:177], v[206:209], v[30:33]
	v_mfma_f32_16x16x32_bf16 v[22:25], v[182:185], v[206:209], v[22:25]
	v_mfma_f32_16x16x32_bf16 v[14:17], v[174:177], v[214:217], v[14:17]
	v_mfma_f32_16x16x32_bf16 v[6:9], v[182:185], v[214:217], v[6:9]
	s_barrier
	s_add_i32 s54, s54, 2
	s_add_u32 s28, s28, 0x100
	s_addc_u32 s29, s29, 0
	s_add_u32 s52, s52, 0x100
	s_addc_u32 s53, s53, 0
	s_cmp_gt_u32 s54, 29
	s_cbranch_scc0 .Lkback_1337
	v_lshl_add_u64 v[244:245], v[220:221], 0, s[12:13]
	s_mov_b32 m0, s42
	s_nop 0
	global_load_lds_dwordx4 v[244:245], off
	v_lshl_add_u64 v[244:245], v[222:223], 0, s[12:13]
	s_mov_b32 m0, s43
	s_nop 0
	global_load_lds_dwordx4 v[244:245], off
	s_setprio 0
	v_mov_b32_e32 v142, v1
	v_mov_b32_e32 v153, v147
	v_mov_b32_e32 v143, v165
	v_mov_b32_e32 v144, v146
	s_lshl_b32 s17, s26, 8
	s_add_i32 s17, s17, s40
	v_add_u32_e32 v142, s17, v144
	v_ashrrev_i32_e32 v143, 31, v142
	v_lshl_add_u64 v[144:145], v[142:143], 2, s[10:11]
	global_load_dword v229, v[144:145], off
	global_load_dword v230, v[144:145], off offset:64
	global_load_dword v231, v[144:145], off offset:128
	global_load_dword v232, v[144:145], off offset:192
	global_load_dword v233, v[144:145], off offset:512
	global_load_dword v234, v[144:145], off offset:576
	global_load_dword v235, v[144:145], off offset:640
	global_load_dword v236, v[144:145], off offset:704
	s_and_b64 vcc, exec, s[14:15]
	s_cbranch_vccz .LBB0_1340
	s_barrier

.LBB0_1448:
	s_and_b64 s[22:23], s[18:19], exec
	s_cselect_b32 s25, s15, s1
	s_cselect_b32 s47, s14, s0
	s_cselect_b32 s48, s17, s21
	s_cselect_b32 s49, s16, s20
	s_add_u32 s0, s0, 0x160080
	s_addc_u32 s1, s1, 0
	s_add_u32 s50, s20, 0x100
	v_mov_b32_e32 v0, 0
	s_addc_u32 s51, s21, 0
	s_mov_b32 s52, -2
	v_mov_b32_e32 v1, v0
	v_mov_b32_e32 v2, v0
	v_mov_b32_e32 v3, v0
	v_mov_b32_e32 v4, v0
	v_mov_b32_e32 v5, v0
	v_mov_b32_e32 v6, v0
	v_mov_b32_e32 v7, v0
	v_mov_b32_e32 v16, v0
	v_mov_b32_e32 v17, v0
	v_mov_b32_e32 v18, v0
	v_mov_b32_e32 v19, v0
	v_mov_b32_e32 v20, v0
	v_mov_b32_e32 v21, v0
	v_mov_b32_e32 v22, v0
	v_mov_b32_e32 v23, v0
	v_mov_b32_e32 v32, v0
	v_mov_b32_e32 v33, v0
	v_mov_b32_e32 v34, v0
	v_mov_b32_e32 v35, v0
	v_mov_b32_e32 v36, v0
	v_mov_b32_e32 v37, v0
	v_mov_b32_e32 v38, v0
	v_mov_b32_e32 v39, v0
	v_mov_b32_e32 v48, v0
	v_mov_b32_e32 v49, v0
	v_mov_b32_e32 v50, v0
	v_mov_b32_e32 v51, v0
	v_mov_b32_e32 v52, v0
	v_mov_b32_e32 v53, v0
	v_mov_b32_e32 v54, v0
	v_mov_b32_e32 v55, v0
	v_mov_b32_e32 v8, v0
	v_mov_b32_e32 v9, v0
	v_mov_b32_e32 v10, v0
	v_mov_b32_e32 v11, v0
	v_mov_b32_e32 v12, v0
	v_mov_b32_e32 v13, v0
	v_mov_b32_e32 v14, v0
	v_mov_b32_e32 v15, v0
	v_mov_b32_e32 v24, v0
	v_mov_b32_e32 v25, v0
	v_mov_b32_e32 v26, v0
	v_mov_b32_e32 v27, v0
	v_mov_b32_e32 v28, v0
	v_mov_b32_e32 v29, v0
	v_mov_b32_e32 v30, v0
	v_mov_b32_e32 v31, v0
	v_mov_b32_e32 v40, v0
	v_mov_b32_e32 v41, v0
	v_mov_b32_e32 v42, v0
	v_mov_b32_e32 v43, v0
	v_mov_b32_e32 v44, v0
	v_mov_b32_e32 v45, v0
	v_mov_b32_e32 v46, v0
	v_mov_b32_e32 v47, v0
	v_mov_b32_e32 v56, v0
	v_mov_b32_e32 v57, v0
	v_mov_b32_e32 v58, v0
	v_mov_b32_e32 v59, v0
	v_mov_b32_e32 v60, v0
	v_mov_b32_e32 v61, v0
	v_mov_b32_e32 v62, v0
	v_mov_b32_e32 v63, v0
	v_mov_b32_e32 v64, v0
	v_mov_b32_e32 v65, v0
	v_mov_b32_e32 v66, v0
	v_mov_b32_e32 v67, v0
	v_mov_b32_e32 v68, v0
	v_mov_b32_e32 v69, v0
	v_mov_b32_e32 v70, v0
	v_mov_b32_e32 v71, v0
	v_mov_b32_e32 v80, v0
	v_mov_b32_e32 v81, v0
	v_mov_b32_e32 v82, v0
	v_mov_b32_e32 v83, v0
	v_mov_b32_e32 v84, v0
	v_mov_b32_e32 v85, v0
	v_mov_b32_e32 v86, v0
	v_mov_b32_e32 v87, v0
	v_mov_b32_e32 v96, v0
	v_mov_b32_e32 v97, v0
	v_mov_b32_e32 v98, v0
	v_mov_b32_e32 v99, v0
	v_mov_b32_e32 v100, v0
	v_mov_b32_e32 v101, v0
	v_mov_b32_e32 v102, v0
	v_mov_b32_e32 v103, v0
	v_mov_b32_e32 v112, v0
	v_mov_b32_e32 v113, v0
	v_mov_b32_e32 v114, v0
	v_mov_b32_e32 v115, v0
	v_mov_b32_e32 v116, v0
	v_mov_b32_e32 v117, v0
	v_mov_b32_e32 v118, v0
	v_mov_b32_e32 v119, v0
	v_mov_b32_e32 v72, v0
	v_mov_b32_e32 v73, v0
	v_mov_b32_e32 v74, v0
	v_mov_b32_e32 v75, v0
	v_mov_b32_e32 v76, v0
	v_mov_b32_e32 v77, v0
	v_mov_b32_e32 v78, v0
	v_mov_b32_e32 v79, v0
	v_mov_b32_e32 v88, v0
	v_mov_b32_e32 v89, v0
	v_mov_b32_e32 v90, v0
	v_mov_b32_e32 v91, v0
	v_mov_b32_e32 v92, v0
	v_mov_b32_e32 v93, v0
	v_mov_b32_e32 v94, v0
	v_mov_b32_e32 v95, v0
	v_mov_b32_e32 v104, v0
	v_mov_b32_e32 v105, v0
	v_mov_b32_e32 v106, v0
	v_mov_b32_e32 v107, v0
	v_mov_b32_e32 v108, v0
	v_mov_b32_e32 v109, v0
	v_mov_b32_e32 v110, v0
	v_mov_b32_e32 v111, v0
	v_mov_b32_e32 v120, v0
	v_mov_b32_e32 v121, v0
	v_mov_b32_e32 v122, v0
	v_mov_b32_e32 v123, v0
	v_mov_b32_e32 v124, v0
	v_mov_b32_e32 v125, v0
	v_mov_b32_e32 v126, v0
	v_mov_b32_e32 v127, v0
	s_and_b64 s[98:99], exec, s[10:11]
	s_cbranch_scc1 .Lsp_p11
	s_setprio 1
.Lsp_p11:
	s_branch .LBB0_1449
.Lkback_1449:
	v_lshl_add_u64 v[244:245], v[218:219], 0, s[8:9]
	s_mov_b32 m0, s39
	s_nop 0
	global_load_lds_dwordx4 v[244:245], off
	v_lshl_add_u64 v[244:245], v[220:221], 0, s[8:9]
	s_mov_b32 m0, s40
	s_nop 0
	global_load_lds_dwordx4 v[244:245], off
.LBB0_1449:
	ds_read_b128 v[140:143], v167
	ds_read_b128 v[144:147], v167 offset:1024
	ds_read_b128 v[148:151], v167 offset:2048
	ds_read_b128 v[152:155], v167 offset:3072
	ds_read_b128 v[156:159], v168
	ds_read_b128 v[172:175], v168 offset:1024
	ds_read_b128 v[176:179], v168 offset:2048
	ds_read_b128 v[180:183], v168 offset:3072
	s_add_u32 s20, s0, 0xffea0080
	s_addc_u32 s21, s1, -1
	s_cmpk_eq_i32 s52, 0x54
	s_cselect_b32 s23, s25, s21
	s_cselect_b32 s22, s47, s20
	s_cselect_b32 s21, s48, s51
	s_cselect_b32 s20, s49, s50
	v_lshl_add_u64 v[160:161], s[0:1], 0, v[136:137]
	s_add_i32 m0, s29, 0xc000
	ds_read_b128 v[184:187], v169
	ds_read_b128 v[188:191], v169 offset:1024
	ds_read_b128 v[192:195], v169 offset:2048
	ds_read_b128 v[196:199], v169 offset:3072
	ds_read_b128 v[200:203], v169 offset:4096
	ds_read_b128 v[204:207], v169 offset:5120
	ds_read_b128 v[208:211], v169 offset:6144
	ds_read_b128 v[212:215], v169 offset:7168
	global_load_lds_dwordx4 v[160:161], off
	v_lshl_add_u64 v[160:161], s[0:1], 0, v[138:139]
	s_add_i32 m0, s29, 0xe000
	s_nop 0
	global_load_lds_dwordx4 v[160:161], off
	s_waitcnt vmcnt(8)
	s_waitcnt lgkmcnt(0)
	s_barrier
	v_mfma_f32_16x16x32_bf16 v[124:127], v[140:143], v[184:187], v[124:127]
	v_mfma_f32_16x16x32_bf16 v[120:123], v[148:151], v[184:187], v[120:123]
	v_mfma_f32_16x16x32_bf16 v[108:111], v[140:143], v[192:195], v[108:111]
	v_mfma_f32_16x16x32_bf16 v[104:107], v[148:151], v[192:195], v[104:107]
	v_mfma_f32_16x16x32_bf16 v[92:95], v[140:143], v[200:203], v[92:95]
	v_mfma_f32_16x16x32_bf16 v[88:91], v[148:151], v[200:203], v[88:91]
	v_mfma_f32_16x16x32_bf16 v[76:79], v[140:143], v[208:211], v[76:79]
	v_mfma_f32_16x16x32_bf16 v[72:75], v[148:151], v[208:211], v[72:75]
	v_mfma_f32_16x16x32_bf16 v[124:127], v[144:147], v[188:191], v[124:127]
	v_mfma_f32_16x16x32_bf16 v[120:123], v[152:155], v[188:191], v[120:123]
	v_mfma_f32_16x16x32_bf16 v[108:111], v[144:147], v[196:199], v[108:111]
	v_mfma_f32_16x16x32_bf16 v[104:107], v[152:155], v[196:199], v[104:107]
	v_mfma_f32_16x16x32_bf16 v[92:95], v[144:147], v[204:207], v[92:95]
	v_mfma_f32_16x16x32_bf16 v[88:91], v[152:155], v[204:207], v[88:91]
	v_mfma_f32_16x16x32_bf16 v[76:79], v[144:147], v[212:215], v[76:79]
	v_mfma_f32_16x16x32_bf16 v[72:75], v[152:155], v[212:215], v[72:75]
	v_mfma_f32_16x16x32_bf16 v[116:119], v[156:159], v[184:187], v[116:119]
	v_mfma_f32_16x16x32_bf16 v[112:115], v[176:179], v[184:187], v[112:115]
	v_mfma_f32_16x16x32_bf16 v[100:103], v[156:159], v[192:195], v[100:103]
	v_mfma_f32_16x16x32_bf16 v[96:99], v[176:179], v[192:195], v[96:99]
	v_mfma_f32_16x16x32_bf16 v[84:87], v[156:159], v[200:203], v[84:87]
	v_mfma_f32_16x16x32_bf16 v[80:83], v[176:179], v[200:203], v[80:83]
	v_mfma_f32_16x16x32_bf16 v[68:71], v[156:159], v[208:211], v[68:71]
	v_mfma_f32_16x16x32_bf16 v[64:67], v[176:179], v[208:211], v[64:67]
	v_mfma_f32_16x16x32_bf16 v[116:119], v[172:175], v[188:191], v[116:119]
	v_mfma_f32_16x16x32_bf16 v[112:115], v[180:183], v[188:191], v[112:115]
	v_mfma_f32_16x16x32_bf16 v[100:103], v[172:175], v[196:199], v[100:103]
	v_mfma_f32_16x16x32_bf16 v[96:99], v[180:183], v[196:199], v[96:99]
	v_mfma_f32_16x16x32_bf16 v[84:87], v[172:175], v[204:207], v[84:87]
	v_mfma_f32_16x16x32_bf16 v[80:83], v[180:183], v[204:207], v[80:83]
	v_mfma_f32_16x16x32_bf16 v[68:71], v[172:175], v[212:215], v[68:71]
	v_mfma_f32_16x16x32_bf16 v[64:67], v[180:183], v[212:215], v[64:67]
	s_barrier
	s_add_i32 s53, s42, s28
	v_lshl_add_u64 v[160:161], s[20:21], 0, v[130:131]
	s_mov_b32 m0, s53
	ds_read_b128 v[184:187], v169 offset:16384
	ds_read_b128 v[188:191], v169 offset:17408
	ds_read_b128 v[192:195], v169 offset:18432
	ds_read_b128 v[196:199], v169 offset:19456
	ds_read_b128 v[200:203], v169 offset:20480
	ds_read_b128 v[204:207], v169 offset:21504
	ds_read_b128 v[208:211], v169 offset:22528
	ds_read_b128 v[212:215], v169 offset:23552
	global_load_lds_dwordx4 v[160:161], off
	s_add_i32 m0, s53, 0x2000
	s_add_u32 s54, s20, 0x160000
	v_lshl_add_u64 v[216:217], s[20:21], 0, v[134:135]
	s_addc_u32 s55, s21, 0
	s_add_i32 s53, s43, s28
	global_load_lds_dwordx4 v[216:217], off
	v_lshl_add_u64 v[218:219], s[54:55], 0, v[130:131]
	s_mov_b32 m0, s53
	v_lshl_add_u64 v[220:221], s[22:23], 0, v[132:133]
	global_load_lds_dwordx4 v[218:219], off
	v_lshl_add_u64 v[218:219], s[54:55], 0, v[134:135]
	s_add_i32 m0, s53, 0x2000
	s_nop 0
	global_load_lds_dwordx4 v[218:219], off
	v_lshl_add_u64 v[218:219], s[22:23], 0, v[128:129]
	s_waitcnt vmcnt(6)
	s_waitcnt lgkmcnt(0)
	s_barrier
	v_mfma_f32_16x16x32_bf16 v[60:63], v[140:143], v[184:187], v[60:63]
	v_mfma_f32_16x16x32_bf16 v[56:59], v[148:151], v[184:187], v[56:59]
	v_mfma_f32_16x16x32_bf16 v[44:47], v[140:143], v[192:195], v[44:47]
	v_mfma_f32_16x16x32_bf16 v[40:43], v[148:151], v[192:195], v[40:43]
	v_mfma_f32_16x16x32_bf16 v[28:31], v[140:143], v[200:203], v[28:31]
	v_mfma_f32_16x16x32_bf16 v[24:27], v[148:151], v[200:203], v[24:27]
	v_mfma_f32_16x16x32_bf16 v[12:15], v[140:143], v[208:211], v[12:15]
	v_mfma_f32_16x16x32_bf16 v[8:11], v[148:151], v[208:211], v[8:11]
	v_mfma_f32_16x16x32_bf16 v[60:63], v[144:147], v[188:191], v[60:63]
	v_mfma_f32_16x16x32_bf16 v[56:59], v[152:155], v[188:191], v[56:59]
	v_mfma_f32_16x16x32_bf16 v[44:47], v[144:147], v[196:199], v[44:47]
	v_mfma_f32_16x16x32_bf16 v[40:43], v[152:155], v[196:199], v[40:43]
	v_mfma_f32_16x16x32_bf16 v[28:31], v[144:147], v[204:207], v[28:31]
	v_mfma_f32_16x16x32_bf16 v[24:27], v[152:155], v[204:207], v[24:27]
	v_mfma_f32_16x16x32_bf16 v[12:15], v[144:147], v[212:215], v[12:15]
	v_mfma_f32_16x16x32_bf16 v[8:11], v[152:155], v[212:215], v[8:11]
	v_mfma_f32_16x16x32_bf16 v[52:55], v[156:159], v[184:187], v[52:55]
	v_mfma_f32_16x16x32_bf16 v[48:51], v[176:179], v[184:187], v[48:51]
	v_mfma_f32_16x16x32_bf16 v[36:39], v[156:159], v[192:195], v[36:39]
	v_mfma_f32_16x16x32_bf16 v[32:35], v[176:179], v[192:195], v[32:35]
	v_mfma_f32_16x16x32_bf16 v[20:23], v[156:159], v[200:203], v[20:23]
	v_mfma_f32_16x16x32_bf16 v[16:19], v[176:179], v[200:203], v[16:19]
	v_mfma_f32_16x16x32_bf16 v[4:7], v[156:159], v[208:211], v[4:7]
	v_mfma_f32_16x16x32_bf16 v[0:3], v[176:179], v[208:211], v[0:3]
	v_mfma_f32_16x16x32_bf16 v[52:55], v[172:175], v[188:191], v[52:55]
	v_mfma_f32_16x16x32_bf16 v[48:51], v[180:183], v[188:191], v[48:51]
	v_mfma_f32_16x16x32_bf16 v[36:39], v[172:175], v[196:199], v[36:39]
	v_mfma_f32_16x16x32_bf16 v[32:35], v[180:183], v[196:199], v[32:35]
	v_mfma_f32_16x16x32_bf16 v[20:23], v[172:175], v[204:207], v[20:23]
	v_mfma_f32_16x16x32_bf16 v[16:19], v[180:183], v[204:207], v[16:19]
	v_mfma_f32_16x16x32_bf16 v[4:7], v[172:175], v[212:215], v[4:7]
	v_mfma_f32_16x16x32_bf16 v[0:3], v[180:183], v[212:215], v[0:3]
	s_barrier
	s_mov_b32 m0, s29
	s_nop 0
	global_load_lds_dwordx4 v[218:219], off
	s_mov_b32 m0, s30
	s_nop 0
	global_load_lds_dwordx4 v[220:221], off
	s_add_i32 s53, 0, 0x18000
	s_add_i32 s54, 0, 0x1c000
	v_add_u32_e32 v152, s53, v166
	v_add_u32_e32 v180, s54, v166
	ds_read_b128 v[140:143], v152
	ds_read_b128 v[144:147], v152 offset:1024
	ds_read_b128 v[148:151], v152 offset:2048
	ds_read_b128 v[152:155], v152 offset:3072
	ds_read_b128 v[156:159], v180
	ds_read_b128 v[172:175], v180 offset:1024
	ds_read_b128 v[176:179], v180 offset:2048
	ds_read_b128 v[180:183], v180 offset:3072
	s_add_u32 s22, s22, 0x160000
	s_addc_u32 s23, s23, 0
	s_mov_b32 m0, s31
	v_lshl_add_u64 v[222:223], s[22:23], 0, v[128:129]
	ds_read_b128 v[184:187], v169 offset:32768
	ds_read_b128 v[188:191], v169 offset:33792
	ds_read_b128 v[192:195], v169 offset:34816
	ds_read_b128 v[196:199], v169 offset:35840
	ds_read_b128 v[200:203], v169 offset:36864
	ds_read_b128 v[204:207], v169 offset:37888
	ds_read_b128 v[208:211], v169 offset:38912
	ds_read_b128 v[212:215], v169 offset:39936
	global_load_lds_dwordx4 v[222:223], off
	v_lshl_add_u64 v[222:223], s[22:23], 0, v[132:133]
	s_mov_b32 m0, s33
	s_nop 0
	global_load_lds_dwordx4 v[222:223], off
	s_waitcnt vmcnt(8)
	s_waitcnt lgkmcnt(0)
	s_barrier
	v_mfma_f32_16x16x32_bf16 v[124:127], v[140:143], v[184:187], v[124:127]
	v_mfma_f32_16x16x32_bf16 v[120:123], v[148:151], v[184:187], v[120:123]
	v_mfma_f32_16x16x32_bf16 v[108:111], v[140:143], v[192:195], v[108:111]
	v_mfma_f32_16x16x32_bf16 v[104:107], v[148:151], v[192:195], v[104:107]
	v_mfma_f32_16x16x32_bf16 v[92:95], v[140:143], v[200:203], v[92:95]
	v_mfma_f32_16x16x32_bf16 v[88:91], v[148:151], v[200:203], v[88:91]
	v_mfma_f32_16x16x32_bf16 v[76:79], v[140:143], v[208:211], v[76:79]
	v_mfma_f32_16x16x32_bf16 v[72:75], v[148:151], v[208:211], v[72:75]
	v_mfma_f32_16x16x32_bf16 v[124:127], v[144:147], v[188:191], v[124:127]
	v_mfma_f32_16x16x32_bf16 v[120:123], v[152:155], v[188:191], v[120:123]
	v_mfma_f32_16x16x32_bf16 v[108:111], v[144:147], v[196:199], v[108:111]
	v_mfma_f32_16x16x32_bf16 v[104:107], v[152:155], v[196:199], v[104:107]
	v_mfma_f32_16x16x32_bf16 v[92:95], v[144:147], v[204:207], v[92:95]
	v_mfma_f32_16x16x32_bf16 v[88:91], v[152:155], v[204:207], v[88:91]
	v_mfma_f32_16x16x32_bf16 v[76:79], v[144:147], v[212:215], v[76:79]
	v_mfma_f32_16x16x32_bf16 v[72:75], v[152:155], v[212:215], v[72:75]
	v_mfma_f32_16x16x32_bf16 v[116:119], v[156:159], v[184:187], v[116:119]
	v_mfma_f32_16x16x32_bf16 v[112:115], v[176:179], v[184:187], v[112:115]
	v_mfma_f32_16x16x32_bf16 v[100:103], v[156:159], v[192:195], v[100:103]
	v_mfma_f32_16x16x32_bf16 v[96:99], v[176:179], v[192:195], v[96:99]
	v_mfma_f32_16x16x32_bf16 v[84:87], v[156:159], v[200:203], v[84:87]
	v_mfma_f32_16x16x32_bf16 v[80:83], v[176:179], v[200:203], v[80:83]
	v_mfma_f32_16x16x32_bf16 v[68:71], v[156:159], v[208:211], v[68:71]
	v_mfma_f32_16x16x32_bf16 v[64:67], v[176:179], v[208:211], v[64:67]
	v_mfma_f32_16x16x32_bf16 v[116:119], v[172:175], v[188:191], v[116:119]
	v_mfma_f32_16x16x32_bf16 v[112:115], v[180:183], v[188:191], v[112:115]
	v_mfma_f32_16x16x32_bf16 v[100:103], v[172:175], v[196:199], v[100:103]
	v_mfma_f32_16x16x32_bf16 v[96:99], v[180:183], v[196:199], v[96:99]
	v_mfma_f32_16x16x32_bf16 v[84:87], v[172:175], v[204:207], v[84:87]
	v_mfma_f32_16x16x32_bf16 v[80:83], v[180:183], v[204:207], v[80:83]
	v_mfma_f32_16x16x32_bf16 v[68:71], v[172:175], v[212:215], v[68:71]
	v_mfma_f32_16x16x32_bf16 v[64:67], v[180:183], v[212:215], v[64:67]
	s_barrier
	s_add_i32 s22, s53, s28
	v_lshl_add_u64 v[160:161], v[160:161], 0, s[8:9]
	s_mov_b32 m0, s22
	ds_read_b128 v[184:187], v169 offset:49152
	ds_read_b128 v[188:191], v169 offset:50176
	ds_read_b128 v[192:195], v169 offset:51200
	ds_read_b128 v[196:199], v169 offset:52224
	ds_read_b128 v[200:203], v169 offset:53248
	ds_read_b128 v[204:207], v169 offset:54272
	ds_read_b128 v[208:211], v169 offset:55296
	ds_read_b128 v[212:215], v169 offset:56320
	global_load_lds_dwordx4 v[160:161], off
	s_add_i32 m0, s22, 0x2000
	s_add_u32 s20, s20, 0x160080
	v_lshl_add_u64 v[160:161], v[216:217], 0, s[8:9]
	s_addc_u32 s21, s21, 0
	s_add_i32 s22, s54, s28
	global_load_lds_dwordx4 v[160:161], off
	v_lshl_add_u64 v[160:161], s[20:21], 0, v[130:131]
	s_mov_b32 m0, s22
	s_nop 0
	global_load_lds_dwordx4 v[160:161], off
	v_lshl_add_u64 v[160:161], s[20:21], 0, v[134:135]
	s_add_i32 m0, s22, 0x2000
	s_nop 0
	global_load_lds_dwordx4 v[160:161], off
	s_waitcnt vmcnt(6)
	s_waitcnt lgkmcnt(0)
	s_barrier
	v_mfma_f32_16x16x32_bf16 v[60:63], v[140:143], v[184:187], v[60:63]
	v_mfma_f32_16x16x32_bf16 v[56:59], v[148:151], v[184:187], v[56:59]
	v_mfma_f32_16x16x32_bf16 v[44:47], v[140:143], v[192:195], v[44:47]
	v_mfma_f32_16x16x32_bf16 v[40:43], v[148:151], v[192:195], v[40:43]
	v_mfma_f32_16x16x32_bf16 v[28:31], v[140:143], v[200:203], v[28:31]
	v_mfma_f32_16x16x32_bf16 v[24:27], v[148:151], v[200:203], v[24:27]
	v_mfma_f32_16x16x32_bf16 v[12:15], v[140:143], v[208:211], v[12:15]
	v_mfma_f32_16x16x32_bf16 v[8:11], v[148:151], v[208:211], v[8:11]
	v_mfma_f32_16x16x32_bf16 v[60:63], v[144:147], v[188:191], v[60:63]
	v_mfma_f32_16x16x32_bf16 v[56:59], v[152:155], v[188:191], v[56:59]
	v_mfma_f32_16x16x32_bf16 v[44:47], v[144:147], v[196:199], v[44:47]
	v_mfma_f32_16x16x32_bf16 v[40:43], v[152:155], v[196:199], v[40:43]
	v_mfma_f32_16x16x32_bf16 v[28:31], v[144:147], v[204:207], v[28:31]
	v_mfma_f32_16x16x32_bf16 v[24:27], v[152:155], v[204:207], v[24:27]
	v_mfma_f32_16x16x32_bf16 v[12:15], v[144:147], v[212:215], v[12:15]
	v_mfma_f32_16x16x32_bf16 v[8:11], v[152:155], v[212:215], v[8:11]
	v_mfma_f32_16x16x32_bf16 v[52:55], v[156:159], v[184:187], v[52:55]
	v_mfma_f32_16x16x32_bf16 v[48:51], v[176:179], v[184:187], v[48:51]
	v_mfma_f32_16x16x32_bf16 v[36:39], v[156:159], v[192:195], v[36:39]
	v_mfma_f32_16x16x32_bf16 v[32:35], v[176:179], v[192:195], v[32:35]
	v_mfma_f32_16x16x32_bf16 v[20:23], v[156:159], v[200:203], v[20:23]
	v_mfma_f32_16x16x32_bf16 v[16:19], v[176:179], v[200:203], v[16:19]
	v_mfma_f32_16x16x32_bf16 v[4:7], v[156:159], v[208:211], v[4:7]
	v_mfma_f32_16x16x32_bf16 v[0:3], v[176:179], v[208:211], v[0:3]
	v_mfma_f32_16x16x32_bf16 v[52:55], v[172:175], v[188:191], v[52:55]
	v_mfma_f32_16x16x32_bf16 v[48:51], v[180:183], v[188:191], v[48:51]
	v_mfma_f32_16x16x32_bf16 v[36:39], v[172:175], v[196:199], v[36:39]
	v_mfma_f32_16x16x32_bf16 v[32:35], v[180:183], v[196:199], v[32:35]
	v_mfma_f32_16x16x32_bf16 v[20:23], v[172:175], v[204:207], v[20:23]
	v_mfma_f32_16x16x32_bf16 v[16:19], v[180:183], v[204:207], v[16:19]
	v_mfma_f32_16x16x32_bf16 v[4:7], v[172:175], v[212:215], v[4:7]
	v_mfma_f32_16x16x32_bf16 v[0:3], v[180:183], v[212:215], v[0:3]
	s_barrier
	s_add_i32 s52, s52, 2
	s_add_u32 s0, s0, 0x100
	s_addc_u32 s1, s1, 0
	s_add_u32 s50, s50, 0x100
	s_addc_u32 s51, s51, 0
	s_cmpk_gt_u32 s52, 0x55
	s_cbranch_scc0 .Lkback_1449
	v_lshl_add_u64 v[244:245], v[218:219], 0, s[8:9]
	s_mov_b32 m0, s39
	s_nop 0
	global_load_lds_dwordx4 v[244:245], off
	v_lshl_add_u64 v[244:245], v[220:221], 0, s[8:9]
	s_mov_b32 m0, s40
	s_nop 0
	global_load_lds_dwordx4 v[244:245], off
	s_setprio 0
	s_and_b64 vcc, exec, s[10:11]
	s_cbranch_vccz .LBB0_1452
	s_barrier
